# softmax exp scale folded into one fma; select sweeps get a no-causal-check body for interior key chunks
# speedup vs baseline: 1.0453x; 1.0038x over previous
; template <int PASS> ...
;     const int sw = (fr >> 1) & 7;
;     const unsigned char* lp = buf + fr * 128;
; #pragma unroll
;     for (int hb = 0; hb < 2; ++hb) {
;         h16x8 kf[8][2];
; #pragma unroll
;         for (int e = 0; e < 8; ++e) { const unsigned char* tp = lp + (hb * 8 + e) * 2048; kf[e][0] = *(const h16x8*)(tp + ((fq ^ sw) << 4)); kf[e][1] = *(const h16x8*)(tp + (((fq + 4) ^ sw) << 4)); }
; #pragma unroll
;         for (int e = 0; e < 8; ++e) { const int T = Tbase + hb * 8 + e;
;             f32x4 a0 = (f32x4){0.f, 0.f, 0.f, 0.f}, a1 = a0;
;             a0 = __builtin_amdgcn_mfma_f32_16x16x32_f16(aq[0][0], kf[e][0], a0, 0, 0, 0); a0 = __builtin_amdgcn_mfma_f32_16x16x32_f16(aq[0][1], kf[e][1], a0, 0, 0, 0);
;             a1 = __builtin_amdgcn_mfma_f32_16x16x32_f16(aq[1][0], kf[e][0], a1, 0, 0, 0); a1 = __builtin_amdgcn_mfma_f32_16x16x32_f16(aq[1][1], kf[e][1], a1, 0, 0, 0);
;             const h16x2 z2 = (h16x2){(h16)0.f, (h16)0.f};
;             const h16x2 r0 = __builtin_elementwise_max(__builtin_bit_cast(h16x2, __builtin_amdgcn_cvt_pkrtz(a0[0], a0[1])), z2), r1 = __builtin_elementwise_max(__builtin_bit_cast(h16x2, __builtin_amdgcn_cvt_pkrtz(a0[2], a0[3])), z2);
;             const h16x2 r2 = __builtin_elementwise_max(__builtin_bit_cast(h16x2, __builtin_amdgcn_cvt_pkrtz(a1[0], a1[1])), z2), r3 = __builtin_elementwise_max(__builtin_bit_cast(h16x2, __builtin_amdgcn_cvt_pkrtz(a1[2], a1[3])), z2);
;             const float sa = __builtin_amdgcn_fdot2(r0, wp[0], __builtin_amdgcn_fdot2(r1, wp[1], __builtin_amdgcn_fdot2(r2, wp[2], __builtin_amdgcn_fdot2(r3, wp[3], 0.f, false), false), false), false);
;             const int key = 16 * T + fr;
;             if (key <= tq) {
;                 const unsigned bin = (unsigned)(int)fminf(fmaxf(sa * 32.f + 128.f, 0.f), 255.f);
;                 if (PASS == 1) { if (bin >= b0) atomicAdd(&myhist[fq * 256 + bin], 1u); }
.LBB0_182:
	s_and_b32 s62, s4, 0x8000
	v_add_u32_e32 v64, s62, v134
	v_add_u32_e32 v122, v64, v135
	v_add_u32_e32 v123, v64, v136
	v_lshlrev_b32_e32 v121, 8, v121
	v_sub_u32_e32 v121, v115, v121
	v_sub_u32_e32 v78, v192, v121
	v_cmp_le_i32_e32 vcc, 0, v78
	s_cmp_eq_u64 vcc, -1
	s_cbranch_scc1 .Lp1_interior
	ds_read_b128 v[32:35], v122
	ds_read_b128 v[36:39], v123
	ds_read_b128 v[40:43], v122 offset:2048
	ds_read_b128 v[44:47], v123 offset:2048
	v_mov_b32_e32 v79, 0x437f0000
	v_mov_b32_e32 v88, 0x50005000
	s_mov_b32 s62, 0x100001
	s_mov_b32 s63, 0x10000100
	v_pk_mul_f16 v80, v193, v88
	v_pk_mul_f16 v81, v194, v88
	v_pk_mul_f16 v82, v195, v88
	v_pk_mul_f16 v83, v196, v88
	v_cndmask_b32_e64 v80, 0, v80, s[62:63]
	v_cndmask_b32_e64 v81, 0, v81, s[62:63]
	v_cndmask_b32_e64 v82, 0, v82, s[62:63]
	v_cndmask_b32_e64 v83, 0, v83, s[62:63]
	v_mov_b32_e32 v84, 0x43000000
	v_mov_b32_e32 v85, 0
	v_mov_b32_e32 v86, 0
	v_mov_b32_e32 v87, 0
	s_waitcnt lgkmcnt(2)
	v_mfma_f32_16x16x32_f16 v[48:51], v[0:3], v[32:35], 0
	v_mfma_f32_16x16x32_f16 v[52:55], v[8:11], v[32:35], 0
	v_mfma_f32_16x16x32_f16 v[48:51], v[4:7], v[36:39], v[48:51]
	v_mfma_f32_16x16x32_f16 v[52:55], v[12:15], v[36:39], v[52:55]
	s_nop 3
	ds_read_b128 v[32:35], v122 offset:4096
	ds_read_b128 v[36:39], v123 offset:4096
	s_waitcnt lgkmcnt(2)
	v_mfma_f32_16x16x32_f16 v[56:59], v[0:3], v[40:43], 0
	v_cvt_pkrtz_f16_f32 v67, v54, v55
	v_cvt_pkrtz_f16_f32 v66, v52, v53
	v_pk_max_f16 v67, v67, 0
	v_pk_max_f16 v66, v66, 0
	v_mfma_f32_16x16x32_f16 v[60:63], v[8:11], v[40:43], 0
	v_cvt_pkrtz_f16_f32 v65, v50, v51
	v_cvt_pkrtz_f16_f32 v64, v48, v49
	v_pk_max_f16 v65, v65, 0
	v_mfma_f32_16x16x32_f16 v[56:59], v[4:7], v[44:47], v[56:59]
	v_pk_max_f16 v64, v64, 0
	v_mfma_f32_16x16x32_f16 v[60:63], v[12:15], v[44:47], v[60:63]
	s_nop 3
	v_mfma_f32_16x16x32_f16 v[68:71], v[80:83], v[64:67], v[84:87]
	ds_read_b128 v[40:43], v122 offset:6144
	ds_read_b128 v[44:47], v123 offset:6144
	s_waitcnt lgkmcnt(2)
	v_mfma_f32_16x16x32_f16 v[48:51], v[0:3], v[32:35], 0
	v_cvt_pkrtz_f16_f32 v67, v62, v63
	v_cvt_pkrtz_f16_f32 v66, v60, v61
	v_pk_max_f16 v67, v67, 0
	v_pk_max_f16 v66, v66, 0
	v_mfma_f32_16x16x32_f16 v[52:55], v[8:11], v[32:35], 0
	v_cvt_pkrtz_f16_f32 v65, v58, v59
	v_cvt_pkrtz_f16_f32 v64, v56, v57
	v_med3_f32 v76, v68, 0, v79
	v_pk_max_f16 v65, v65, 0
	v_mfma_f32_16x16x32_f16 v[48:51], v[4:7], v[36:39], v[48:51]
	v_pk_max_f16 v64, v64, 0
	v_cvt_u32_f32_e32 v76, v76
	v_cmp_le_i32_e32 vcc, -240, v78
	v_mfma_f32_16x16x32_f16 v[52:55], v[12:15], v[36:39], v[52:55]
	v_lshl_add_u32 v77, v76, 2, v139
	s_and_b64 exec, exec, vcc
	ds_add_u32 v77, v212
	s_mov_b64 exec, -1
	v_mfma_f32_16x16x32_f16 v[72:75], v[80:83], v[64:67], v[84:87]
	ds_read_b128 v[32:35], v122 offset:8192
	ds_read_b128 v[36:39], v123 offset:8192
	s_waitcnt lgkmcnt(3)
	v_mfma_f32_16x16x32_f16 v[56:59], v[0:3], v[40:43], 0
	v_cvt_pkrtz_f16_f32 v67, v54, v55
	v_cvt_pkrtz_f16_f32 v66, v52, v53
	v_pk_max_f16 v67, v67, 0
	v_pk_max_f16 v66, v66, 0
	v_mfma_f32_16x16x32_f16 v[60:63], v[8:11], v[40:43], 0
	v_cvt_pkrtz_f16_f32 v65, v50, v51
	v_cvt_pkrtz_f16_f32 v64, v48, v49
	v_med3_f32 v76, v72, 0, v79
	v_pk_max_f16 v65, v65, 0
	v_mfma_f32_16x16x32_f16 v[56:59], v[4:7], v[44:47], v[56:59]
	v_pk_max_f16 v64, v64, 0
	v_cvt_u32_f32_e32 v76, v76
	v_cmp_le_i32_e32 vcc, -224, v78
	v_mfma_f32_16x16x32_f16 v[60:63], v[12:15], v[44:47], v[60:63]
	v_lshl_add_u32 v77, v76, 2, v139
	s_and_b64 exec, exec, vcc
	ds_add_u32 v77, v212
	s_mov_b64 exec, -1
	v_mfma_f32_16x16x32_f16 v[68:71], v[80:83], v[64:67], v[84:87]
	ds_read_b128 v[40:43], v122 offset:10240
	ds_read_b128 v[44:47], v123 offset:10240
	s_waitcnt lgkmcnt(3)
	v_mfma_f32_16x16x32_f16 v[48:51], v[0:3], v[32:35], 0
	v_cvt_pkrtz_f16_f32 v67, v62, v63
	v_cvt_pkrtz_f16_f32 v66, v60, v61
	v_pk_max_f16 v67, v67, 0
	v_pk_max_f16 v66, v66, 0
	v_mfma_f32_16x16x32_f16 v[52:55], v[8:11], v[32:35], 0
	v_cvt_pkrtz_f16_f32 v65, v58, v59
	v_cvt_pkrtz_f16_f32 v64, v56, v57
	v_med3_f32 v76, v68, 0, v79
	v_pk_max_f16 v65, v65, 0
	v_mfma_f32_16x16x32_f16 v[48:51], v[4:7], v[36:39], v[48:51]
	v_pk_max_f16 v64, v64, 0
	v_cvt_u32_f32_e32 v76, v76
	v_cmp_le_i32_e32 vcc, -208, v78
	v_mfma_f32_16x16x32_f16 v[52:55], v[12:15], v[36:39], v[52:55]
	v_lshl_add_u32 v77, v76, 2, v139
	s_and_b64 exec, exec, vcc
	ds_add_u32 v77, v212
	s_mov_b64 exec, -1
	v_mfma_f32_16x16x32_f16 v[72:75], v[80:83], v[64:67], v[84:87]
	ds_read_b128 v[32:35], v122 offset:12288
	ds_read_b128 v[36:39], v123 offset:12288
	s_waitcnt lgkmcnt(3)
	v_mfma_f32_16x16x32_f16 v[56:59], v[0:3], v[40:43], 0
	v_cvt_pkrtz_f16_f32 v67, v54, v55
	v_cvt_pkrtz_f16_f32 v66, v52, v53
	v_pk_max_f16 v67, v67, 0
	v_pk_max_f16 v66, v66, 0
	v_mfma_f32_16x16x32_f16 v[60:63], v[8:11], v[40:43], 0
	v_cvt_pkrtz_f16_f32 v65, v50, v51
	v_cvt_pkrtz_f16_f32 v64, v48, v49
	v_med3_f32 v76, v72, 0, v79
	v_pk_max_f16 v65, v65, 0
	v_mfma_f32_16x16x32_f16 v[56:59], v[4:7], v[44:47], v[56:59]
	v_pk_max_f16 v64, v64, 0
	v_cvt_u32_f32_e32 v76, v76
	v_cmp_le_i32_e32 vcc, -192, v78
	v_mfma_f32_16x16x32_f16 v[60:63], v[12:15], v[44:47], v[60:63]
	v_lshl_add_u32 v77, v76, 2, v139
	s_and_b64 exec, exec, vcc
	ds_add_u32 v77, v212
	s_mov_b64 exec, -1
	v_mfma_f32_16x16x32_f16 v[68:71], v[80:83], v[64:67], v[84:87]
	ds_read_b128 v[40:43], v122 offset:14336
	ds_read_b128 v[44:47], v123 offset:14336
	s_waitcnt lgkmcnt(3)
; template <int PASS> ...
;     ...
;         for (int e = 0; e < 8; ++e) { const int T = Tbase + hb * 8 + e;
;             f32x4 a0 = (f32x4){0.f, 0.f, 0.f, 0.f}, a1 = a0;
;             a0 = __builtin_amdgcn_mfma_f32_16x16x32_f16(aq[0][0], kf[e][0], a0, 0, 0, 0); a0 = __builtin_amdgcn_mfma_f32_16x16x32_f16(aq[0][1], kf[e][1], a0, 0, 0, 0);
;             a1 = __builtin_amdgcn_mfma_f32_16x16x32_f16(aq[1][0], kf[e][0], a1, 0, 0, 0); a1 = __builtin_amdgcn_mfma_f32_16x16x32_f16(aq[1][1], kf[e][1], a1, 0, 0, 0);
;             const h16x2 z2 = (h16x2){(h16)0.f, (h16)0.f};
;             const h16x2 r0 = __builtin_elementwise_max(__builtin_bit_cast(h16x2, __builtin_amdgcn_cvt_pkrtz(a0[0], a0[1])), z2), r1 = __builtin_elementwise_max(__builtin_bit_cast(h16x2, __builtin_amdgcn_cvt_pkrtz(a0[2], a0[3])), z2);
;             const h16x2 r2 = __builtin_elementwise_max(__builtin_bit_cast(h16x2, __builtin_amdgcn_cvt_pkrtz(a1[0], a1[1])), z2), r3 = __builtin_elementwise_max(__builtin_bit_cast(h16x2, __builtin_amdgcn_cvt_pkrtz(a1[2], a1[3])), z2);
;             const float sa = __builtin_amdgcn_fdot2(r0, wp[0], __builtin_amdgcn_fdot2(r1, wp[1], __builtin_amdgcn_fdot2(r2, wp[2], __builtin_amdgcn_fdot2(r3, wp[3], 0.f, false), false), false), false);
;             const int key = 16 * T + fr;
;             if (key <= tq) {
;                 const unsigned bin = (unsigned)(int)fminf(fmaxf(sa * 32.f + 128.f, 0.f), 255.f);
;                 if (PASS == 1) { if (bin >= b0) atomicAdd(&myhist[fq * 256 + bin], 1u); }
	v_mfma_f32_16x16x32_f16 v[48:51], v[0:3], v[32:35], 0
	v_cvt_pkrtz_f16_f32 v67, v62, v63
	v_cvt_pkrtz_f16_f32 v66, v60, v61
	v_pk_max_f16 v67, v67, 0
	v_pk_max_f16 v66, v66, 0
	v_mfma_f32_16x16x32_f16 v[52:55], v[8:11], v[32:35], 0
	v_cvt_pkrtz_f16_f32 v65, v58, v59
	v_cvt_pkrtz_f16_f32 v64, v56, v57
	v_med3_f32 v76, v68, 0, v79
	v_pk_max_f16 v65, v65, 0
	v_mfma_f32_16x16x32_f16 v[48:51], v[4:7], v[36:39], v[48:51]
	v_pk_max_f16 v64, v64, 0
	v_cvt_u32_f32_e32 v76, v76
	v_cmp_le_i32_e32 vcc, -176, v78
	v_mfma_f32_16x16x32_f16 v[52:55], v[12:15], v[36:39], v[52:55]
	v_lshl_add_u32 v77, v76, 2, v139
	s_and_b64 exec, exec, vcc
	ds_add_u32 v77, v212
	s_mov_b64 exec, -1
	v_mfma_f32_16x16x32_f16 v[72:75], v[80:83], v[64:67], v[84:87]
	ds_read_b128 v[32:35], v122 offset:16384
	ds_read_b128 v[36:39], v123 offset:16384
	s_waitcnt lgkmcnt(3)
	v_mfma_f32_16x16x32_f16 v[56:59], v[0:3], v[40:43], 0
	v_cvt_pkrtz_f16_f32 v67, v54, v55
	v_cvt_pkrtz_f16_f32 v66, v52, v53
	v_pk_max_f16 v67, v67, 0
	v_pk_max_f16 v66, v66, 0
	v_mfma_f32_16x16x32_f16 v[60:63], v[8:11], v[40:43], 0
	v_cvt_pkrtz_f16_f32 v65, v50, v51
	v_cvt_pkrtz_f16_f32 v64, v48, v49
	v_med3_f32 v76, v72, 0, v79
	v_pk_max_f16 v65, v65, 0
	v_mfma_f32_16x16x32_f16 v[56:59], v[4:7], v[44:47], v[56:59]
	v_pk_max_f16 v64, v64, 0
	v_cvt_u32_f32_e32 v76, v76
	v_cmp_le_i32_e32 vcc, -160, v78
	v_mfma_f32_16x16x32_f16 v[60:63], v[12:15], v[44:47], v[60:63]
	v_lshl_add_u32 v77, v76, 2, v139
	s_and_b64 exec, exec, vcc
	ds_add_u32 v77, v212
	s_mov_b64 exec, -1
	v_mfma_f32_16x16x32_f16 v[68:71], v[80:83], v[64:67], v[84:87]
	ds_read_b128 v[40:43], v122 offset:18432
	ds_read_b128 v[44:47], v123 offset:18432
	s_waitcnt lgkmcnt(3)
	v_mfma_f32_16x16x32_f16 v[48:51], v[0:3], v[32:35], 0
	v_cvt_pkrtz_f16_f32 v67, v62, v63
	v_cvt_pkrtz_f16_f32 v66, v60, v61
	v_pk_max_f16 v67, v67, 0
	v_pk_max_f16 v66, v66, 0
	v_mfma_f32_16x16x32_f16 v[52:55], v[8:11], v[32:35], 0
	v_cvt_pkrtz_f16_f32 v65, v58, v59
	v_cvt_pkrtz_f16_f32 v64, v56, v57
	v_med3_f32 v76, v68, 0, v79
	v_pk_max_f16 v65, v65, 0
	v_mfma_f32_16x16x32_f16 v[48:51], v[4:7], v[36:39], v[48:51]
	v_pk_max_f16 v64, v64, 0
	v_cvt_u32_f32_e32 v76, v76
	v_cmp_le_i32_e32 vcc, -144, v78
	v_mfma_f32_16x16x32_f16 v[52:55], v[12:15], v[36:39], v[52:55]
	v_lshl_add_u32 v77, v76, 2, v139
	s_and_b64 exec, exec, vcc
	ds_add_u32 v77, v212
	s_mov_b64 exec, -1
	v_mfma_f32_16x16x32_f16 v[72:75], v[80:83], v[64:67], v[84:87]
	ds_read_b128 v[32:35], v122 offset:20480
	ds_read_b128 v[36:39], v123 offset:20480
	s_waitcnt lgkmcnt(3)
	v_mfma_f32_16x16x32_f16 v[56:59], v[0:3], v[40:43], 0
	v_cvt_pkrtz_f16_f32 v67, v54, v55
	v_cvt_pkrtz_f16_f32 v66, v52, v53
	v_pk_max_f16 v67, v67, 0
	v_pk_max_f16 v66, v66, 0
	v_mfma_f32_16x16x32_f16 v[60:63], v[8:11], v[40:43], 0
	v_cvt_pkrtz_f16_f32 v65, v50, v51
	v_cvt_pkrtz_f16_f32 v64, v48, v49
	v_med3_f32 v76, v72, 0, v79
	v_pk_max_f16 v65, v65, 0
	v_mfma_f32_16x16x32_f16 v[56:59], v[4:7], v[44:47], v[56:59]
	v_pk_max_f16 v64, v64, 0
	v_cvt_u32_f32_e32 v76, v76
	v_cmp_le_i32_e32 vcc, -128, v78
	v_mfma_f32_16x16x32_f16 v[60:63], v[12:15], v[44:47], v[60:63]
	v_lshl_add_u32 v77, v76, 2, v139
	s_and_b64 exec, exec, vcc
	ds_add_u32 v77, v212
	s_mov_b64 exec, -1
	v_mfma_f32_16x16x32_f16 v[68:71], v[80:83], v[64:67], v[84:87]
	ds_read_b128 v[40:43], v122 offset:22528
	ds_read_b128 v[44:47], v123 offset:22528
	s_waitcnt lgkmcnt(3)
	v_mfma_f32_16x16x32_f16 v[48:51], v[0:3], v[32:35], 0
	v_cvt_pkrtz_f16_f32 v67, v62, v63
	v_cvt_pkrtz_f16_f32 v66, v60, v61
	v_pk_max_f16 v67, v67, 0
	v_pk_max_f16 v66, v66, 0
	v_mfma_f32_16x16x32_f16 v[52:55], v[8:11], v[32:35], 0
	v_cvt_pkrtz_f16_f32 v65, v58, v59
	v_cvt_pkrtz_f16_f32 v64, v56, v57
	v_med3_f32 v76, v68, 0, v79
	v_pk_max_f16 v65, v65, 0
	v_mfma_f32_16x16x32_f16 v[48:51], v[4:7], v[36:39], v[48:51]
	v_pk_max_f16 v64, v64, 0
	v_cvt_u32_f32_e32 v76, v76
	v_cmp_le_i32_e32 vcc, -112, v78
	v_mfma_f32_16x16x32_f16 v[52:55], v[12:15], v[36:39], v[52:55]
	v_lshl_add_u32 v77, v76, 2, v139
	s_and_b64 exec, exec, vcc
	ds_add_u32 v77, v212
	s_mov_b64 exec, -1
	v_mfma_f32_16x16x32_f16 v[72:75], v[80:83], v[64:67], v[84:87]
	ds_read_b128 v[32:35], v122 offset:24576
	ds_read_b128 v[36:39], v123 offset:24576
	s_waitcnt lgkmcnt(3)
	v_mfma_f32_16x16x32_f16 v[56:59], v[0:3], v[40:43], 0
	v_cvt_pkrtz_f16_f32 v67, v54, v55
	v_cvt_pkrtz_f16_f32 v66, v52, v53
	v_pk_max_f16 v67, v67, 0
	v_pk_max_f16 v66, v66, 0
	v_mfma_f32_16x16x32_f16 v[60:63], v[8:11], v[40:43], 0
	v_cvt_pkrtz_f16_f32 v65, v50, v51
	v_cvt_pkrtz_f16_f32 v64, v48, v49
	v_med3_f32 v76, v72, 0, v79
	v_pk_max_f16 v65, v65, 0
	v_mfma_f32_16x16x32_f16 v[56:59], v[4:7], v[44:47], v[56:59]
	v_pk_max_f16 v64, v64, 0
	v_cvt_u32_f32_e32 v76, v76
	v_cmp_le_i32_e32 vcc, -96, v78
	v_mfma_f32_16x16x32_f16 v[60:63], v[12:15], v[44:47], v[60:63]
	v_lshl_add_u32 v77, v76, 2, v139
	s_and_b64 exec, exec, vcc
	ds_add_u32 v77, v212
	s_mov_b64 exec, -1
	v_mfma_f32_16x16x32_f16 v[68:71], v[80:83], v[64:67], v[84:87]
	ds_read_b128 v[40:43], v122 offset:26624
	ds_read_b128 v[44:47], v123 offset:26624
	s_waitcnt lgkmcnt(3)
	v_mfma_f32_16x16x32_f16 v[48:51], v[0:3], v[32:35], 0
	v_cvt_pkrtz_f16_f32 v67, v62, v63
	v_cvt_pkrtz_f16_f32 v66, v60, v61
	v_pk_max_f16 v67, v67, 0
	v_pk_max_f16 v66, v66, 0
	v_mfma_f32_16x16x32_f16 v[52:55], v[8:11], v[32:35], 0
	v_cvt_pkrtz_f16_f32 v65, v58, v59
	v_cvt_pkrtz_f16_f32 v64, v56, v57
	v_med3_f32 v76, v68, 0, v79
	v_pk_max_f16 v65, v65, 0
	v_mfma_f32_16x16x32_f16 v[48:51], v[4:7], v[36:39], v[48:51]
	v_pk_max_f16 v64, v64, 0
	v_cvt_u32_f32_e32 v76, v76
	v_cmp_le_i32_e32 vcc, -80, v78
	v_mfma_f32_16x16x32_f16 v[52:55], v[12:15], v[36:39], v[52:55]
	v_lshl_add_u32 v77, v76, 2, v139
	s_and_b64 exec, exec, vcc
	ds_add_u32 v77, v212
	s_mov_b64 exec, -1
	v_mfma_f32_16x16x32_f16 v[72:75], v[80:83], v[64:67], v[84:87]
	ds_read_b128 v[32:35], v122 offset:28672
	ds_read_b128 v[36:39], v123 offset:28672
	s_waitcnt lgkmcnt(3)
; template <int PASS> ...
;     ...
;         for (int e = 0; e < 8; ++e) { const int T = Tbase + hb * 8 + e;
;             f32x4 a0 = (f32x4){0.f, 0.f, 0.f, 0.f}, a1 = a0;
;             a0 = __builtin_amdgcn_mfma_f32_16x16x32_f16(aq[0][0], kf[e][0], a0, 0, 0, 0); a0 = __builtin_amdgcn_mfma_f32_16x16x32_f16(aq[0][1], kf[e][1], a0, 0, 0, 0);
;             a1 = __builtin_amdgcn_mfma_f32_16x16x32_f16(aq[1][0], kf[e][0], a1, 0, 0, 0); a1 = __builtin_amdgcn_mfma_f32_16x16x32_f16(aq[1][1], kf[e][1], a1, 0, 0, 0);
;             const h16x2 z2 = (h16x2){(h16)0.f, (h16)0.f};
;             const h16x2 r0 = __builtin_elementwise_max(__builtin_bit_cast(h16x2, __builtin_amdgcn_cvt_pkrtz(a0[0], a0[1])), z2), r1 = __builtin_elementwise_max(__builtin_bit_cast(h16x2, __builtin_amdgcn_cvt_pkrtz(a0[2], a0[3])), z2);
;             const h16x2 r2 = __builtin_elementwise_max(__builtin_bit_cast(h16x2, __builtin_amdgcn_cvt_pkrtz(a1[0], a1[1])), z2), r3 = __builtin_elementwise_max(__builtin_bit_cast(h16x2, __builtin_amdgcn_cvt_pkrtz(a1[2], a1[3])), z2);
;             const float sa = __builtin_amdgcn_fdot2(r0, wp[0], __builtin_amdgcn_fdot2(r1, wp[1], __builtin_amdgcn_fdot2(r2, wp[2], __builtin_amdgcn_fdot2(r3, wp[3], 0.f, false), false), false), false);
;             const int key = 16 * T + fr;
;             if (key <= tq) {
;                 const unsigned bin = (unsigned)(int)fminf(fmaxf(sa * 32.f + 128.f, 0.f), 255.f);
;                 if (PASS == 1) { if (bin >= b0) atomicAdd(&myhist[fq * 256 + bin], 1u); }
	v_mfma_f32_16x16x32_f16 v[56:59], v[0:3], v[40:43], 0
	v_cvt_pkrtz_f16_f32 v67, v54, v55
	v_cvt_pkrtz_f16_f32 v66, v52, v53
	v_pk_max_f16 v67, v67, 0
	v_pk_max_f16 v66, v66, 0
	v_mfma_f32_16x16x32_f16 v[60:63], v[8:11], v[40:43], 0
	v_cvt_pkrtz_f16_f32 v65, v50, v51
	v_cvt_pkrtz_f16_f32 v64, v48, v49
	v_med3_f32 v76, v72, 0, v79
	v_pk_max_f16 v65, v65, 0
	v_mfma_f32_16x16x32_f16 v[56:59], v[4:7], v[44:47], v[56:59]
	v_pk_max_f16 v64, v64, 0
	v_cvt_u32_f32_e32 v76, v76
	v_cmp_le_i32_e32 vcc, -64, v78
	v_mfma_f32_16x16x32_f16 v[60:63], v[12:15], v[44:47], v[60:63]
	v_lshl_add_u32 v77, v76, 2, v139
	s_and_b64 exec, exec, vcc
	ds_add_u32 v77, v212
	s_mov_b64 exec, -1
	v_mfma_f32_16x16x32_f16 v[68:71], v[80:83], v[64:67], v[84:87]
	ds_read_b128 v[40:43], v122 offset:30720
	ds_read_b128 v[44:47], v123 offset:30720
	s_waitcnt lgkmcnt(3)
	v_mfma_f32_16x16x32_f16 v[48:51], v[0:3], v[32:35], 0
	v_cvt_pkrtz_f16_f32 v67, v62, v63
	v_cvt_pkrtz_f16_f32 v66, v60, v61
	v_pk_max_f16 v67, v67, 0
	v_pk_max_f16 v66, v66, 0
	v_mfma_f32_16x16x32_f16 v[52:55], v[8:11], v[32:35], 0
	v_cvt_pkrtz_f16_f32 v65, v58, v59
	v_cvt_pkrtz_f16_f32 v64, v56, v57
	v_med3_f32 v76, v68, 0, v79
	v_pk_max_f16 v65, v65, 0
	v_mfma_f32_16x16x32_f16 v[48:51], v[4:7], v[36:39], v[48:51]
	v_pk_max_f16 v64, v64, 0
	v_cvt_u32_f32_e32 v76, v76
	v_cmp_le_i32_e32 vcc, -48, v78
	v_mfma_f32_16x16x32_f16 v[52:55], v[12:15], v[36:39], v[52:55]
	v_lshl_add_u32 v77, v76, 2, v139
	s_and_b64 exec, exec, vcc
	ds_add_u32 v77, v212
	s_mov_b64 exec, -1
	v_mfma_f32_16x16x32_f16 v[72:75], v[80:83], v[64:67], v[84:87]
	s_nop 3
	s_waitcnt lgkmcnt(1)
	v_mfma_f32_16x16x32_f16 v[56:59], v[0:3], v[40:43], 0
	v_cvt_pkrtz_f16_f32 v67, v54, v55
	v_cvt_pkrtz_f16_f32 v66, v52, v53
	v_pk_max_f16 v67, v67, 0
	v_pk_max_f16 v66, v66, 0
	v_mfma_f32_16x16x32_f16 v[60:63], v[8:11], v[40:43], 0
	v_cvt_pkrtz_f16_f32 v65, v50, v51
	v_cvt_pkrtz_f16_f32 v64, v48, v49
	v_med3_f32 v76, v72, 0, v79
	v_pk_max_f16 v65, v65, 0
	v_mfma_f32_16x16x32_f16 v[56:59], v[4:7], v[44:47], v[56:59]
	v_pk_max_f16 v64, v64, 0
	v_cvt_u32_f32_e32 v76, v76
	v_cmp_le_i32_e32 vcc, -32, v78
	v_mfma_f32_16x16x32_f16 v[60:63], v[12:15], v[44:47], v[60:63]
	v_lshl_add_u32 v77, v76, 2, v139
	s_and_b64 exec, exec, vcc
	ds_add_u32 v77, v212
	s_mov_b64 exec, -1
	v_mfma_f32_16x16x32_f16 v[68:71], v[80:83], v[64:67], v[84:87]
	s_nop 3
	v_cvt_pkrtz_f16_f32 v67, v62, v63
	v_cvt_pkrtz_f16_f32 v66, v60, v61
	v_pk_max_f16 v67, v67, 0
	v_pk_max_f16 v66, v66, 0
	v_cvt_pkrtz_f16_f32 v65, v58, v59
	v_cvt_pkrtz_f16_f32 v64, v56, v57
	v_med3_f32 v76, v68, 0, v79
	v_pk_max_f16 v65, v65, 0
	v_pk_max_f16 v64, v64, 0
	v_cvt_u32_f32_e32 v76, v76
	v_cmp_le_i32_e32 vcc, -16, v78
	v_lshl_add_u32 v77, v76, 2, v139
	s_and_b64 exec, exec, vcc
	ds_add_u32 v77, v212
	s_mov_b64 exec, -1
	v_mfma_f32_16x16x32_f16 v[72:75], v[80:83], v[64:67], v[84:87]
	s_nop 7
	s_nop 3
	v_med3_f32 v76, v72, 0, v79
	v_cvt_u32_f32_e32 v76, v76
	v_cmp_le_i32_e32 vcc, 0, v78
	v_lshl_add_u32 v77, v76, 2, v139
	s_and_b64 exec, exec, vcc
	ds_add_u32 v77, v212
	s_mov_b64 exec, -1
	s_branch .LBB0_239
.Lp1_interior:
	ds_read_b128 v[32:35], v122
	ds_read_b128 v[36:39], v123
	ds_read_b128 v[40:43], v122 offset:2048
	ds_read_b128 v[44:47], v123 offset:2048
	v_mov_b32_e32 v79, 0x437f0000
	v_mov_b32_e32 v88, 0x50005000
	s_mov_b32 s62, 0x100001
	s_mov_b32 s63, 0x10000100
	v_pk_mul_f16 v80, v193, v88
	v_pk_mul_f16 v81, v194, v88
	v_pk_mul_f16 v82, v195, v88
	v_pk_mul_f16 v83, v196, v88
	v_cndmask_b32_e64 v80, 0, v80, s[62:63]
	v_cndmask_b32_e64 v81, 0, v81, s[62:63]
	v_cndmask_b32_e64 v82, 0, v82, s[62:63]
	v_cndmask_b32_e64 v83, 0, v83, s[62:63]
	v_mov_b32_e32 v84, 0x43000000
	v_mov_b32_e32 v85, 0
	v_mov_b32_e32 v86, 0
	v_mov_b32_e32 v87, 0
	s_waitcnt lgkmcnt(2)
	v_mfma_f32_16x16x32_f16 v[48:51], v[0:3], v[32:35], 0
	v_mfma_f32_16x16x32_f16 v[52:55], v[8:11], v[32:35], 0
	v_mfma_f32_16x16x32_f16 v[48:51], v[4:7], v[36:39], v[48:51]
	v_mfma_f32_16x16x32_f16 v[52:55], v[12:15], v[36:39], v[52:55]
	s_nop 3
	ds_read_b128 v[32:35], v122 offset:4096
	ds_read_b128 v[36:39], v123 offset:4096
	s_waitcnt lgkmcnt(2)
	v_mfma_f32_16x16x32_f16 v[56:59], v[0:3], v[40:43], 0
	v_cvt_pkrtz_f16_f32 v67, v54, v55
	v_cvt_pkrtz_f16_f32 v66, v52, v53
	v_pk_max_f16 v67, v67, 0
	v_pk_max_f16 v66, v66, 0
	v_mfma_f32_16x16x32_f16 v[60:63], v[8:11], v[40:43], 0
	v_cvt_pkrtz_f16_f32 v65, v50, v51
	v_cvt_pkrtz_f16_f32 v64, v48, v49
	v_pk_max_f16 v65, v65, 0
	v_mfma_f32_16x16x32_f16 v[56:59], v[4:7], v[44:47], v[56:59]
	v_pk_max_f16 v64, v64, 0
	v_mfma_f32_16x16x32_f16 v[60:63], v[12:15], v[44:47], v[60:63]
	s_nop 3
	v_mfma_f32_16x16x32_f16 v[68:71], v[80:83], v[64:67], v[84:87]
	ds_read_b128 v[40:43], v122 offset:6144
	ds_read_b128 v[44:47], v123 offset:6144
	s_waitcnt lgkmcnt(2)
	v_mfma_f32_16x16x32_f16 v[48:51], v[0:3], v[32:35], 0
	v_cvt_pkrtz_f16_f32 v67, v62, v63
	v_cvt_pkrtz_f16_f32 v66, v60, v61
	v_pk_max_f16 v67, v67, 0
	v_pk_max_f16 v66, v66, 0
	v_mfma_f32_16x16x32_f16 v[52:55], v[8:11], v[32:35], 0
	v_cvt_pkrtz_f16_f32 v65, v58, v59
	v_cvt_pkrtz_f16_f32 v64, v56, v57
	v_med3_f32 v76, v68, 0, v79
	v_pk_max_f16 v65, v65, 0
	v_mfma_f32_16x16x32_f16 v[48:51], v[4:7], v[36:39], v[48:51]
	v_pk_max_f16 v64, v64, 0
	v_cvt_u32_f32_e32 v76, v76
	v_mfma_f32_16x16x32_f16 v[52:55], v[12:15], v[36:39], v[52:55]
	v_lshl_add_u32 v77, v76, 2, v139
	s_nop 0
	ds_add_u32 v77, v212
	s_nop 0
	s_nop 0
	v_mfma_f32_16x16x32_f16 v[72:75], v[80:83], v[64:67], v[84:87]
	ds_read_b128 v[32:35], v122 offset:8192
	ds_read_b128 v[36:39], v123 offset:8192
	s_waitcnt lgkmcnt(3)
; template <int PASS> ...
;     ...
;         for (int e = 0; e < 8; ++e) { const int T = Tbase + hb * 8 + e;
;             f32x4 a0 = (f32x4){0.f, 0.f, 0.f, 0.f}, a1 = a0;
;             a0 = __builtin_amdgcn_mfma_f32_16x16x32_f16(aq[0][0], kf[e][0], a0, 0, 0, 0); a0 = __builtin_amdgcn_mfma_f32_16x16x32_f16(aq[0][1], kf[e][1], a0, 0, 0, 0);
;             a1 = __builtin_amdgcn_mfma_f32_16x16x32_f16(aq[1][0], kf[e][0], a1, 0, 0, 0); a1 = __builtin_amdgcn_mfma_f32_16x16x32_f16(aq[1][1], kf[e][1], a1, 0, 0, 0);
;             const h16x2 z2 = (h16x2){(h16)0.f, (h16)0.f};
;             const h16x2 r0 = __builtin_elementwise_max(__builtin_bit_cast(h16x2, __builtin_amdgcn_cvt_pkrtz(a0[0], a0[1])), z2), r1 = __builtin_elementwise_max(__builtin_bit_cast(h16x2, __builtin_amdgcn_cvt_pkrtz(a0[2], a0[3])), z2);
;             const h16x2 r2 = __builtin_elementwise_max(__builtin_bit_cast(h16x2, __builtin_amdgcn_cvt_pkrtz(a1[0], a1[1])), z2), r3 = __builtin_elementwise_max(__builtin_bit_cast(h16x2, __builtin_amdgcn_cvt_pkrtz(a1[2], a1[3])), z2);
;             const float sa = __builtin_amdgcn_fdot2(r0, wp[0], __builtin_amdgcn_fdot2(r1, wp[1], __builtin_amdgcn_fdot2(r2, wp[2], __builtin_amdgcn_fdot2(r3, wp[3], 0.f, false), false), false), false);
;             const int key = 16 * T + fr;
;             if (key <= tq) {
;                 const unsigned bin = (unsigned)(int)fminf(fmaxf(sa * 32.f + 128.f, 0.f), 255.f);
;                 if (PASS == 1) { if (bin >= b0) atomicAdd(&myhist[fq * 256 + bin], 1u); }
	v_mfma_f32_16x16x32_f16 v[56:59], v[0:3], v[40:43], 0
	v_cvt_pkrtz_f16_f32 v67, v54, v55
	v_cvt_pkrtz_f16_f32 v66, v52, v53
	v_pk_max_f16 v67, v67, 0
	v_pk_max_f16 v66, v66, 0
	v_mfma_f32_16x16x32_f16 v[60:63], v[8:11], v[40:43], 0
	v_cvt_pkrtz_f16_f32 v65, v50, v51
	v_cvt_pkrtz_f16_f32 v64, v48, v49
	v_med3_f32 v76, v72, 0, v79
	v_pk_max_f16 v65, v65, 0
	v_mfma_f32_16x16x32_f16 v[56:59], v[4:7], v[44:47], v[56:59]
	v_pk_max_f16 v64, v64, 0
	v_cvt_u32_f32_e32 v76, v76
	v_mfma_f32_16x16x32_f16 v[60:63], v[12:15], v[44:47], v[60:63]
	v_lshl_add_u32 v77, v76, 2, v139
	s_nop 0
	ds_add_u32 v77, v212
	s_nop 0
	s_nop 0
	v_mfma_f32_16x16x32_f16 v[68:71], v[80:83], v[64:67], v[84:87]
	ds_read_b128 v[40:43], v122 offset:10240
	ds_read_b128 v[44:47], v123 offset:10240
	s_waitcnt lgkmcnt(3)
	v_mfma_f32_16x16x32_f16 v[48:51], v[0:3], v[32:35], 0
	v_cvt_pkrtz_f16_f32 v67, v62, v63
	v_cvt_pkrtz_f16_f32 v66, v60, v61
	v_pk_max_f16 v67, v67, 0
	v_pk_max_f16 v66, v66, 0
	v_mfma_f32_16x16x32_f16 v[52:55], v[8:11], v[32:35], 0
	v_cvt_pkrtz_f16_f32 v65, v58, v59
	v_cvt_pkrtz_f16_f32 v64, v56, v57
	v_med3_f32 v76, v68, 0, v79
	v_pk_max_f16 v65, v65, 0
	v_mfma_f32_16x16x32_f16 v[48:51], v[4:7], v[36:39], v[48:51]
	v_pk_max_f16 v64, v64, 0
	v_cvt_u32_f32_e32 v76, v76
	v_mfma_f32_16x16x32_f16 v[52:55], v[12:15], v[36:39], v[52:55]
	v_lshl_add_u32 v77, v76, 2, v139
	s_nop 0
	ds_add_u32 v77, v212
	s_nop 0
	s_nop 0
	v_mfma_f32_16x16x32_f16 v[72:75], v[80:83], v[64:67], v[84:87]
	ds_read_b128 v[32:35], v122 offset:12288
	ds_read_b128 v[36:39], v123 offset:12288
	s_waitcnt lgkmcnt(3)
	v_mfma_f32_16x16x32_f16 v[56:59], v[0:3], v[40:43], 0
	v_cvt_pkrtz_f16_f32 v67, v54, v55
	v_cvt_pkrtz_f16_f32 v66, v52, v53
	v_pk_max_f16 v67, v67, 0
	v_pk_max_f16 v66, v66, 0
	v_mfma_f32_16x16x32_f16 v[60:63], v[8:11], v[40:43], 0
	v_cvt_pkrtz_f16_f32 v65, v50, v51
	v_cvt_pkrtz_f16_f32 v64, v48, v49
	v_med3_f32 v76, v72, 0, v79
	v_pk_max_f16 v65, v65, 0
	v_mfma_f32_16x16x32_f16 v[56:59], v[4:7], v[44:47], v[56:59]
	v_pk_max_f16 v64, v64, 0
	v_cvt_u32_f32_e32 v76, v76
	v_mfma_f32_16x16x32_f16 v[60:63], v[12:15], v[44:47], v[60:63]
	v_lshl_add_u32 v77, v76, 2, v139
	s_nop 0
	ds_add_u32 v77, v212
	s_nop 0
	s_nop 0
	v_mfma_f32_16x16x32_f16 v[68:71], v[80:83], v[64:67], v[84:87]
	ds_read_b128 v[40:43], v122 offset:14336
	ds_read_b128 v[44:47], v123 offset:14336
	s_waitcnt lgkmcnt(3)
	v_mfma_f32_16x16x32_f16 v[48:51], v[0:3], v[32:35], 0
	v_cvt_pkrtz_f16_f32 v67, v62, v63
	v_cvt_pkrtz_f16_f32 v66, v60, v61
	v_pk_max_f16 v67, v67, 0
	v_pk_max_f16 v66, v66, 0
	v_mfma_f32_16x16x32_f16 v[52:55], v[8:11], v[32:35], 0
	v_cvt_pkrtz_f16_f32 v65, v58, v59
	v_cvt_pkrtz_f16_f32 v64, v56, v57
	v_med3_f32 v76, v68, 0, v79
	v_pk_max_f16 v65, v65, 0
	v_mfma_f32_16x16x32_f16 v[48:51], v[4:7], v[36:39], v[48:51]
	v_pk_max_f16 v64, v64, 0
	v_cvt_u32_f32_e32 v76, v76
	v_mfma_f32_16x16x32_f16 v[52:55], v[12:15], v[36:39], v[52:55]
	v_lshl_add_u32 v77, v76, 2, v139
	s_nop 0
	ds_add_u32 v77, v212
	s_nop 0
	s_nop 0
	v_mfma_f32_16x16x32_f16 v[72:75], v[80:83], v[64:67], v[84:87]
	ds_read_b128 v[32:35], v122 offset:16384
	ds_read_b128 v[36:39], v123 offset:16384
	s_waitcnt lgkmcnt(3)
	v_mfma_f32_16x16x32_f16 v[56:59], v[0:3], v[40:43], 0
	v_cvt_pkrtz_f16_f32 v67, v54, v55
	v_cvt_pkrtz_f16_f32 v66, v52, v53
	v_pk_max_f16 v67, v67, 0
	v_pk_max_f16 v66, v66, 0
	v_mfma_f32_16x16x32_f16 v[60:63], v[8:11], v[40:43], 0
	v_cvt_pkrtz_f16_f32 v65, v50, v51
	v_cvt_pkrtz_f16_f32 v64, v48, v49
	v_med3_f32 v76, v72, 0, v79
	v_pk_max_f16 v65, v65, 0
	v_mfma_f32_16x16x32_f16 v[56:59], v[4:7], v[44:47], v[56:59]
	v_pk_max_f16 v64, v64, 0
	v_cvt_u32_f32_e32 v76, v76
	v_mfma_f32_16x16x32_f16 v[60:63], v[12:15], v[44:47], v[60:63]
	v_lshl_add_u32 v77, v76, 2, v139
	s_nop 0
	ds_add_u32 v77, v212
	s_nop 0
	s_nop 0
	v_mfma_f32_16x16x32_f16 v[68:71], v[80:83], v[64:67], v[84:87]
	ds_read_b128 v[40:43], v122 offset:18432
	ds_read_b128 v[44:47], v123 offset:18432
	s_waitcnt lgkmcnt(3)
	v_mfma_f32_16x16x32_f16 v[48:51], v[0:3], v[32:35], 0
	v_cvt_pkrtz_f16_f32 v67, v62, v63
	v_cvt_pkrtz_f16_f32 v66, v60, v61
	v_pk_max_f16 v67, v67, 0
	v_pk_max_f16 v66, v66, 0
	v_mfma_f32_16x16x32_f16 v[52:55], v[8:11], v[32:35], 0
	v_cvt_pkrtz_f16_f32 v65, v58, v59
	v_cvt_pkrtz_f16_f32 v64, v56, v57
	v_med3_f32 v76, v68, 0, v79
	v_pk_max_f16 v65, v65, 0
	v_mfma_f32_16x16x32_f16 v[48:51], v[4:7], v[36:39], v[48:51]
	v_pk_max_f16 v64, v64, 0
	v_cvt_u32_f32_e32 v76, v76
	v_mfma_f32_16x16x32_f16 v[52:55], v[12:15], v[36:39], v[52:55]
	v_lshl_add_u32 v77, v76, 2, v139
	s_nop 0
	ds_add_u32 v77, v212
	s_nop 0
	s_nop 0
	v_mfma_f32_16x16x32_f16 v[72:75], v[80:83], v[64:67], v[84:87]
	ds_read_b128 v[32:35], v122 offset:20480
	ds_read_b128 v[36:39], v123 offset:20480
	s_waitcnt lgkmcnt(3)
	v_mfma_f32_16x16x32_f16 v[56:59], v[0:3], v[40:43], 0
	v_cvt_pkrtz_f16_f32 v67, v54, v55
	v_cvt_pkrtz_f16_f32 v66, v52, v53
	v_pk_max_f16 v67, v67, 0
	v_pk_max_f16 v66, v66, 0
	v_mfma_f32_16x16x32_f16 v[60:63], v[8:11], v[40:43], 0
	v_cvt_pkrtz_f16_f32 v65, v50, v51
	v_cvt_pkrtz_f16_f32 v64, v48, v49
	v_med3_f32 v76, v72, 0, v79
	v_pk_max_f16 v65, v65, 0
	v_mfma_f32_16x16x32_f16 v[56:59], v[4:7], v[44:47], v[56:59]
	v_pk_max_f16 v64, v64, 0
	v_cvt_u32_f32_e32 v76, v76
	v_mfma_f32_16x16x32_f16 v[60:63], v[12:15], v[44:47], v[60:63]
	v_lshl_add_u32 v77, v76, 2, v139
	s_nop 0
	ds_add_u32 v77, v212
	s_nop 0
	s_nop 0
	v_mfma_f32_16x16x32_f16 v[68:71], v[80:83], v[64:67], v[84:87]
	ds_read_b128 v[40:43], v122 offset:22528
	ds_read_b128 v[44:47], v123 offset:22528
	s_waitcnt lgkmcnt(3)
; template <int PASS> ...
;     ...
;         for (int e = 0; e < 8; ++e) { const int T = Tbase + hb * 8 + e;
;             f32x4 a0 = (f32x4){0.f, 0.f, 0.f, 0.f}, a1 = a0;
;             a0 = __builtin_amdgcn_mfma_f32_16x16x32_f16(aq[0][0], kf[e][0], a0, 0, 0, 0); a0 = __builtin_amdgcn_mfma_f32_16x16x32_f16(aq[0][1], kf[e][1], a0, 0, 0, 0);
;             a1 = __builtin_amdgcn_mfma_f32_16x16x32_f16(aq[1][0], kf[e][0], a1, 0, 0, 0); a1 = __builtin_amdgcn_mfma_f32_16x16x32_f16(aq[1][1], kf[e][1], a1, 0, 0, 0);
;             const h16x2 z2 = (h16x2){(h16)0.f, (h16)0.f};
;             const h16x2 r0 = __builtin_elementwise_max(__builtin_bit_cast(h16x2, __builtin_amdgcn_cvt_pkrtz(a0[0], a0[1])), z2), r1 = __builtin_elementwise_max(__builtin_bit_cast(h16x2, __builtin_amdgcn_cvt_pkrtz(a0[2], a0[3])), z2);
;             const h16x2 r2 = __builtin_elementwise_max(__builtin_bit_cast(h16x2, __builtin_amdgcn_cvt_pkrtz(a1[0], a1[1])), z2), r3 = __builtin_elementwise_max(__builtin_bit_cast(h16x2, __builtin_amdgcn_cvt_pkrtz(a1[2], a1[3])), z2);
;             const float sa = __builtin_amdgcn_fdot2(r0, wp[0], __builtin_amdgcn_fdot2(r1, wp[1], __builtin_amdgcn_fdot2(r2, wp[2], __builtin_amdgcn_fdot2(r3, wp[3], 0.f, false), false), false), false);
;             const int key = 16 * T + fr;
;             if (key <= tq) {
;                 const unsigned bin = (unsigned)(int)fminf(fmaxf(sa * 32.f + 128.f, 0.f), 255.f);
;                 if (PASS == 1) { if (bin >= b0) atomicAdd(&myhist[fq * 256 + bin], 1u); }
	v_mfma_f32_16x16x32_f16 v[48:51], v[0:3], v[32:35], 0
	v_cvt_pkrtz_f16_f32 v67, v62, v63
	v_cvt_pkrtz_f16_f32 v66, v60, v61
	v_pk_max_f16 v67, v67, 0
	v_pk_max_f16 v66, v66, 0
	v_mfma_f32_16x16x32_f16 v[52:55], v[8:11], v[32:35], 0
	v_cvt_pkrtz_f16_f32 v65, v58, v59
	v_cvt_pkrtz_f16_f32 v64, v56, v57
	v_med3_f32 v76, v68, 0, v79
	v_pk_max_f16 v65, v65, 0
	v_mfma_f32_16x16x32_f16 v[48:51], v[4:7], v[36:39], v[48:51]
	v_pk_max_f16 v64, v64, 0
	v_cvt_u32_f32_e32 v76, v76
	v_mfma_f32_16x16x32_f16 v[52:55], v[12:15], v[36:39], v[52:55]
	v_lshl_add_u32 v77, v76, 2, v139
	s_nop 0
	ds_add_u32 v77, v212
	s_nop 0
	s_nop 0
	v_mfma_f32_16x16x32_f16 v[72:75], v[80:83], v[64:67], v[84:87]
	ds_read_b128 v[32:35], v122 offset:24576
	ds_read_b128 v[36:39], v123 offset:24576
	s_waitcnt lgkmcnt(3)
	v_mfma_f32_16x16x32_f16 v[56:59], v[0:3], v[40:43], 0
	v_cvt_pkrtz_f16_f32 v67, v54, v55
	v_cvt_pkrtz_f16_f32 v66, v52, v53
	v_pk_max_f16 v67, v67, 0
	v_pk_max_f16 v66, v66, 0
	v_mfma_f32_16x16x32_f16 v[60:63], v[8:11], v[40:43], 0
	v_cvt_pkrtz_f16_f32 v65, v50, v51
	v_cvt_pkrtz_f16_f32 v64, v48, v49
	v_med3_f32 v76, v72, 0, v79
	v_pk_max_f16 v65, v65, 0
	v_mfma_f32_16x16x32_f16 v[56:59], v[4:7], v[44:47], v[56:59]
	v_pk_max_f16 v64, v64, 0
	v_cvt_u32_f32_e32 v76, v76
	v_mfma_f32_16x16x32_f16 v[60:63], v[12:15], v[44:47], v[60:63]
	v_lshl_add_u32 v77, v76, 2, v139
	s_nop 0
	ds_add_u32 v77, v212
	s_nop 0
	s_nop 0
	v_mfma_f32_16x16x32_f16 v[68:71], v[80:83], v[64:67], v[84:87]
	ds_read_b128 v[40:43], v122 offset:26624
	ds_read_b128 v[44:47], v123 offset:26624
	s_waitcnt lgkmcnt(3)
	v_mfma_f32_16x16x32_f16 v[48:51], v[0:3], v[32:35], 0
	v_cvt_pkrtz_f16_f32 v67, v62, v63
	v_cvt_pkrtz_f16_f32 v66, v60, v61
	v_pk_max_f16 v67, v67, 0
	v_pk_max_f16 v66, v66, 0
	v_mfma_f32_16x16x32_f16 v[52:55], v[8:11], v[32:35], 0
	v_cvt_pkrtz_f16_f32 v65, v58, v59
	v_cvt_pkrtz_f16_f32 v64, v56, v57
	v_med3_f32 v76, v68, 0, v79
	v_pk_max_f16 v65, v65, 0
	v_mfma_f32_16x16x32_f16 v[48:51], v[4:7], v[36:39], v[48:51]
	v_pk_max_f16 v64, v64, 0
	v_cvt_u32_f32_e32 v76, v76
	v_mfma_f32_16x16x32_f16 v[52:55], v[12:15], v[36:39], v[52:55]
	v_lshl_add_u32 v77, v76, 2, v139
	s_nop 0
	ds_add_u32 v77, v212
	s_nop 0
	s_nop 0
	v_mfma_f32_16x16x32_f16 v[72:75], v[80:83], v[64:67], v[84:87]
	ds_read_b128 v[32:35], v122 offset:28672
	ds_read_b128 v[36:39], v123 offset:28672
	s_waitcnt lgkmcnt(3)
	v_mfma_f32_16x16x32_f16 v[56:59], v[0:3], v[40:43], 0
	v_cvt_pkrtz_f16_f32 v67, v54, v55
	v_cvt_pkrtz_f16_f32 v66, v52, v53
	v_pk_max_f16 v67, v67, 0
	v_pk_max_f16 v66, v66, 0
	v_mfma_f32_16x16x32_f16 v[60:63], v[8:11], v[40:43], 0
	v_cvt_pkrtz_f16_f32 v65, v50, v51
	v_cvt_pkrtz_f16_f32 v64, v48, v49
	v_med3_f32 v76, v72, 0, v79
	v_pk_max_f16 v65, v65, 0
	v_mfma_f32_16x16x32_f16 v[56:59], v[4:7], v[44:47], v[56:59]
	v_pk_max_f16 v64, v64, 0
	v_cvt_u32_f32_e32 v76, v76
	v_mfma_f32_16x16x32_f16 v[60:63], v[12:15], v[44:47], v[60:63]
	v_lshl_add_u32 v77, v76, 2, v139
	s_nop 0
	ds_add_u32 v77, v212
	s_nop 0
	s_nop 0
	v_mfma_f32_16x16x32_f16 v[68:71], v[80:83], v[64:67], v[84:87]
	ds_read_b128 v[40:43], v122 offset:30720
	ds_read_b128 v[44:47], v123 offset:30720
	s_waitcnt lgkmcnt(3)
	v_mfma_f32_16x16x32_f16 v[48:51], v[0:3], v[32:35], 0
	v_cvt_pkrtz_f16_f32 v67, v62, v63
	v_cvt_pkrtz_f16_f32 v66, v60, v61
	v_pk_max_f16 v67, v67, 0
	v_pk_max_f16 v66, v66, 0
	v_mfma_f32_16x16x32_f16 v[52:55], v[8:11], v[32:35], 0
	v_cvt_pkrtz_f16_f32 v65, v58, v59
	v_cvt_pkrtz_f16_f32 v64, v56, v57
	v_med3_f32 v76, v68, 0, v79
	v_pk_max_f16 v65, v65, 0
	v_mfma_f32_16x16x32_f16 v[48:51], v[4:7], v[36:39], v[48:51]
	v_pk_max_f16 v64, v64, 0
	v_cvt_u32_f32_e32 v76, v76
	v_mfma_f32_16x16x32_f16 v[52:55], v[12:15], v[36:39], v[52:55]
	v_lshl_add_u32 v77, v76, 2, v139
	s_nop 0
	ds_add_u32 v77, v212
	s_nop 0
	s_nop 0
	v_mfma_f32_16x16x32_f16 v[72:75], v[80:83], v[64:67], v[84:87]
	s_nop 3
	s_waitcnt lgkmcnt(1)
	v_mfma_f32_16x16x32_f16 v[56:59], v[0:3], v[40:43], 0
	v_cvt_pkrtz_f16_f32 v67, v54, v55
	v_cvt_pkrtz_f16_f32 v66, v52, v53
	v_pk_max_f16 v67, v67, 0
	v_pk_max_f16 v66, v66, 0
	v_mfma_f32_16x16x32_f16 v[60:63], v[8:11], v[40:43], 0
	v_cvt_pkrtz_f16_f32 v65, v50, v51
	v_cvt_pkrtz_f16_f32 v64, v48, v49
	v_med3_f32 v76, v72, 0, v79
	v_pk_max_f16 v65, v65, 0
	v_mfma_f32_16x16x32_f16 v[56:59], v[4:7], v[44:47], v[56:59]
	v_pk_max_f16 v64, v64, 0
	v_cvt_u32_f32_e32 v76, v76
	v_mfma_f32_16x16x32_f16 v[60:63], v[12:15], v[44:47], v[60:63]
	v_lshl_add_u32 v77, v76, 2, v139
	s_nop 0
	ds_add_u32 v77, v212
	s_nop 0
	s_nop 0
	v_mfma_f32_16x16x32_f16 v[68:71], v[80:83], v[64:67], v[84:87]
	s_nop 3
	v_cvt_pkrtz_f16_f32 v67, v62, v63
	v_cvt_pkrtz_f16_f32 v66, v60, v61
	v_pk_max_f16 v67, v67, 0
	v_pk_max_f16 v66, v66, 0
	v_cvt_pkrtz_f16_f32 v65, v58, v59
	v_cvt_pkrtz_f16_f32 v64, v56, v57
	v_med3_f32 v76, v68, 0, v79
	v_pk_max_f16 v65, v65, 0
	v_pk_max_f16 v64, v64, 0
	v_cvt_u32_f32_e32 v76, v76
	v_lshl_add_u32 v77, v76, 2, v139
	s_nop 0
	ds_add_u32 v77, v212
	s_nop 0
	s_nop 0
	v_mfma_f32_16x16x32_f16 v[72:75], v[80:83], v[64:67], v[84:87]
	s_nop 7
	s_nop 3
	v_med3_f32 v76, v72, 0, v79
	v_cvt_u32_f32_e32 v76, v76
	v_lshl_add_u32 v77, v76, 2, v139
	s_nop 0
	ds_add_u32 v77, v212
	s_nop 0
	s_nop 0
	s_branch .LBB0_239

; template <int PASS> ...
;     ...
;         for (int e = 0; e < 8; ++e) { const int T = Tbase + hb * 8 + e;
;             f32x4 a0 = (f32x4){0.f, 0.f, 0.f, 0.f}, a1 = a0;
;             a0 = __builtin_amdgcn_mfma_f32_16x16x32_f16(aq[0][0], kf[e][0], a0, 0, 0, 0); a0 = __builtin_amdgcn_mfma_f32_16x16x32_f16(aq[0][1], kf[e][1], a0, 0, 0, 0);
;             a1 = __builtin_amdgcn_mfma_f32_16x16x32_f16(aq[1][0], kf[e][0], a1, 0, 0, 0); a1 = __builtin_amdgcn_mfma_f32_16x16x32_f16(aq[1][1], kf[e][1], a1, 0, 0, 0);
;             const h16x2 z2 = (h16x2){(h16)0.f, (h16)0.f};
;             const h16x2 r0 = __builtin_elementwise_max(__builtin_bit_cast(h16x2, __builtin_amdgcn_cvt_pkrtz(a0[0], a0[1])), z2), r1 = __builtin_elementwise_max(__builtin_bit_cast(h16x2, __builtin_amdgcn_cvt_pkrtz(a0[2], a0[3])), z2);
;             const h16x2 r2 = __builtin_elementwise_max(__builtin_bit_cast(h16x2, __builtin_amdgcn_cvt_pkrtz(a1[0], a1[1])), z2), r3 = __builtin_elementwise_max(__builtin_bit_cast(h16x2, __builtin_amdgcn_cvt_pkrtz(a1[2], a1[3])), z2);
;             const float sa = __builtin_amdgcn_fdot2(r0, wp[0], __builtin_amdgcn_fdot2(r1, wp[1], __builtin_amdgcn_fdot2(r2, wp[2], __builtin_amdgcn_fdot2(r3, wp[3], 0.f, false), false), false), false);
;             const int key = 16 * T + fr;
;             if (key <= tq) {
;                 const unsigned bin = (unsigned)(int)fminf(fmaxf(sa * 32.f + 128.f, 0.f), 255.f);
;                 if (PASS == 1) { if (bin >= b0) atomicAdd(&myhist[fq * 256 + bin], 1u); }
;                 else {
;                     if (bin > b0) { const unsigned pos = atomicAdd(&myctl[fq * 4 + 2], 1u); ((unsigned short*)myhist)[fq * 256 + (pos & 255u)] = (unsigned short)key; }
;                     else if (bin == b0) { const unsigned c = atomicAdd(&myctl[fq * 4 + 3], 1u);
;                         if (c < 128u) { float s = 0.f;
; #pragma unroll
;                             for (int r = 0; r < 4; ++r) s += wv[r] * fmaxf(a0[r], 0.f) + wv[4 + r] * fmaxf(a1[r], 0.f);
;                             s = fminf(fmaxf(s, -3.99f), 3.99f);
;                             mycand[(fq * 128 + c) * 2] = (unsigned)((s + 4.f) * 536870912.f); mycand[(fq * 128 + c) * 2 + 1] = (unsigned)key; } }
;                 }
.LBB0_293:
	s_and_b32 s4, s85, 0x8000
	v_add_u32_e32 v72, s4, v134
	v_add_u32_e32 v118, v72, v135
	v_add_u32_e32 v119, v72, v136
	ds_read_b128 v[32:35], v118
	ds_read_b128 v[36:39], v119
	ds_read_b128 v[40:43], v118 offset:2048
	ds_read_b128 v[44:47], v119 offset:2048
	v_lshlrev_b32_e32 v116, 8, v116
	v_sub_u32_e32 v117, v121, v116
	v_sub_u32_e32 v93, v192, v117
	v_cvt_f32_u32_e32 v94, v120
	v_cmp_eq_u32_e32 vcc, 0, v120
	v_add_f32_e32 v95, 1.0, v94
	v_mov_b32_e32 v92, 0
	v_mov_b32_e32 v123, 0xff800000
	v_cndmask_b32_e32 v94, v94, v123, vcc
	v_cmp_lt_u32_e32 vcc, 0xfe, v120
	v_mov_b32_e32 v123, 0x7f800000
	v_subrev_u32_e32 v122, 0x100, v117
	v_cndmask_b32_e32 v95, v95, v123, vcc
	v_bfrev_b32_e32 v123, 1
	v_cmp_le_i32_e32 vcc, 240, v93
	s_cmp_eq_u64 vcc, -1
	s_cbranch_scc1 .Lp2_interior
	v_mov_b32_e32 v202, 0x50005000
	s_mov_b32 s60, 0x100001
	s_mov_b32 s61, 0x10000100
	v_pk_mul_f16 v84, v193, v202
	v_pk_mul_f16 v85, v194, v202
	v_pk_mul_f16 v86, v195, v202
	v_pk_mul_f16 v87, v196, v202
	v_cndmask_b32_e64 v84, 0, v84, s[60:61]
	v_cndmask_b32_e64 v85, 0, v85, s[60:61]
	v_cndmask_b32_e64 v86, 0, v86, s[60:61]
	v_cndmask_b32_e64 v87, 0, v87, s[60:61]
	v_mov_b32_e32 v88, 0x43000000
	v_mov_b32_e32 v89, 0
	v_mov_b32_e32 v90, 0
	v_mov_b32_e32 v91, 0
	s_waitcnt lgkmcnt(2)
	v_mfma_f32_16x16x32_f16 v[48:51], v[0:3], v[32:35], 0
	v_mfma_f32_16x16x32_f16 v[52:55], v[8:11], v[32:35], 0
	v_mfma_f32_16x16x32_f16 v[48:51], v[4:7], v[36:39], v[48:51]
	v_mfma_f32_16x16x32_f16 v[52:55], v[12:15], v[36:39], v[52:55]
	s_nop 3
	ds_read_b128 v[32:35], v118 offset:4096
	ds_read_b128 v[36:39], v119 offset:4096
	s_waitcnt lgkmcnt(2)
	v_mfma_f32_16x16x32_f16 v[56:59], v[0:3], v[40:43], 0
	v_cvt_pkrtz_f16_f32 v75, v54, v55
	v_cvt_pkrtz_f16_f32 v74, v52, v53
	v_pk_max_f16 v75, v75, 0
	v_pk_max_f16 v74, v74, 0
	v_mfma_f32_16x16x32_f16 v[60:63], v[8:11], v[40:43], 0
	v_cvt_pkrtz_f16_f32 v73, v50, v51
	v_cvt_pkrtz_f16_f32 v72, v48, v49
	v_pk_max_f16 v73, v73, 0
	v_mfma_f32_16x16x32_f16 v[56:59], v[4:7], v[44:47], v[56:59]
	v_pk_max_f16 v72, v72, 0
	v_mfma_f32_16x16x32_f16 v[60:63], v[12:15], v[44:47], v[60:63]
	s_nop 3
	v_mfma_f32_16x16x32_f16 v[76:79], v[84:87], v[72:75], v[88:91]
	ds_read_b128 v[40:43], v118 offset:6144
	ds_read_b128 v[44:47], v119 offset:6144
	s_waitcnt lgkmcnt(2)
	v_mfma_f32_16x16x32_f16 v[64:67], v[0:3], v[32:35], 0
	v_cvt_pkrtz_f16_f32 v75, v62, v63
	v_cvt_pkrtz_f16_f32 v74, v60, v61
	v_pk_max_f16 v75, v75, 0
	v_pk_max_f16 v74, v74, 0
	v_mfma_f32_16x16x32_f16 v[68:71], v[8:11], v[32:35], 0
	v_cvt_pkrtz_f16_f32 v73, v58, v59
	v_cvt_pkrtz_f16_f32 v72, v56, v57
	v_cmp_le_i32_e32 vcc, 0, v93
	v_pk_max_f16 v73, v73, 0
	v_mfma_f32_16x16x32_f16 v[64:67], v[4:7], v[36:39], v[64:67]
	v_pk_max_f16 v72, v72, 0
	v_cmp_le_f32_e64 s[60:61], v95, v76
	v_cmp_le_f32_e64 s[62:63], v94, v76
	v_mfma_f32_16x16x32_f16 v[68:71], v[12:15], v[36:39], v[68:71]
	v_mfma_f32_16x16x32_f16 v[80:83], v[84:87], v[72:75], v[88:91]
	s_and_b64 s[62:63], s[62:63], vcc
	s_and_b64 vcc, vcc, s[60:61]
	v_addc_co_u32_e32 v92, vcc, v92, v92, vcc
	s_andn2_b64 s[62:63], s[62:63], s[60:61]
	s_cbranch_scc1 .Lp2d_slow0

; template <int PASS> ...
;     ...
;         for (int e = 0; e < 8; ++e) { const int T = Tbase + hb * 8 + e;
;             f32x4 a0 = (f32x4){0.f, 0.f, 0.f, 0.f}, a1 = a0;
;             a0 = __builtin_amdgcn_mfma_f32_16x16x32_f16(aq[0][0], kf[e][0], a0, 0, 0, 0); a0 = __builtin_amdgcn_mfma_f32_16x16x32_f16(aq[0][1], kf[e][1], a0, 0, 0, 0);
;             a1 = __builtin_amdgcn_mfma_f32_16x16x32_f16(aq[1][0], kf[e][0], a1, 0, 0, 0); a1 = __builtin_amdgcn_mfma_f32_16x16x32_f16(aq[1][1], kf[e][1], a1, 0, 0, 0);
;             const h16x2 z2 = (h16x2){(h16)0.f, (h16)0.f};
;             const h16x2 r0 = __builtin_elementwise_max(__builtin_bit_cast(h16x2, __builtin_amdgcn_cvt_pkrtz(a0[0], a0[1])), z2), r1 = __builtin_elementwise_max(__builtin_bit_cast(h16x2, __builtin_amdgcn_cvt_pkrtz(a0[2], a0[3])), z2);
;             const h16x2 r2 = __builtin_elementwise_max(__builtin_bit_cast(h16x2, __builtin_amdgcn_cvt_pkrtz(a1[0], a1[1])), z2), r3 = __builtin_elementwise_max(__builtin_bit_cast(h16x2, __builtin_amdgcn_cvt_pkrtz(a1[2], a1[3])), z2);
;             const float sa = __builtin_amdgcn_fdot2(r0, wp[0], __builtin_amdgcn_fdot2(r1, wp[1], __builtin_amdgcn_fdot2(r2, wp[2], __builtin_amdgcn_fdot2(r3, wp[3], 0.f, false), false), false), false);
;             const int key = 16 * T + fr;
;             if (key <= tq) {
;                 const unsigned bin = (unsigned)(int)fminf(fmaxf(sa * 32.f + 128.f, 0.f), 255.f);
;                 if (PASS == 1) { if (bin >= b0) atomicAdd(&myhist[fq * 256 + bin], 1u); }
;                 else {
;                     if (bin > b0) { const unsigned pos = atomicAdd(&myctl[fq * 4 + 2], 1u); ((unsigned short*)myhist)[fq * 256 + (pos & 255u)] = (unsigned short)key; }
;                     else if (bin == b0) { const unsigned c = atomicAdd(&myctl[fq * 4 + 3], 1u);
;                         if (c < 128u) { float s = 0.f;
; #pragma unroll
;                             for (int r = 0; r < 4; ++r) s += wv[r] * fmaxf(a0[r], 0.f) + wv[4 + r] * fmaxf(a1[r], 0.f);
;                             s = fminf(fmaxf(s, -3.99f), 3.99f);
;                             mycand[(fq * 128 + c) * 2] = (unsigned)((s + 4.f) * 536870912.f); mycand[(fq * 128 + c) * 2 + 1] = (unsigned)key; } }
;                 }
.Lp2_interior:
	v_mov_b32_e32 v202, 0x50005000
	s_mov_b32 s60, 0x100001
	s_mov_b32 s61, 0x10000100
	v_pk_mul_f16 v84, v193, v202
	v_pk_mul_f16 v85, v194, v202
	v_pk_mul_f16 v86, v195, v202
	v_pk_mul_f16 v87, v196, v202
	v_cndmask_b32_e64 v84, 0, v84, s[60:61]
	v_cndmask_b32_e64 v85, 0, v85, s[60:61]
	v_cndmask_b32_e64 v86, 0, v86, s[60:61]
	v_cndmask_b32_e64 v87, 0, v87, s[60:61]
	v_mov_b32_e32 v88, 0x43000000
	v_mov_b32_e32 v89, 0
	v_mov_b32_e32 v90, 0
	v_mov_b32_e32 v91, 0
	s_waitcnt lgkmcnt(2)
	v_mfma_f32_16x16x32_f16 v[48:51], v[0:3], v[32:35], 0
	v_mfma_f32_16x16x32_f16 v[52:55], v[8:11], v[32:35], 0
	v_mfma_f32_16x16x32_f16 v[48:51], v[4:7], v[36:39], v[48:51]
	v_mfma_f32_16x16x32_f16 v[52:55], v[12:15], v[36:39], v[52:55]
	s_nop 3
	ds_read_b128 v[32:35], v118 offset:4096
	ds_read_b128 v[36:39], v119 offset:4096
	s_waitcnt lgkmcnt(2)
	v_mfma_f32_16x16x32_f16 v[56:59], v[0:3], v[40:43], 0
	v_cvt_pkrtz_f16_f32 v75, v54, v55
	v_cvt_pkrtz_f16_f32 v74, v52, v53
	v_pk_max_f16 v75, v75, 0
	v_pk_max_f16 v74, v74, 0
	v_mfma_f32_16x16x32_f16 v[60:63], v[8:11], v[40:43], 0
	v_cvt_pkrtz_f16_f32 v73, v50, v51
	v_cvt_pkrtz_f16_f32 v72, v48, v49
	v_pk_max_f16 v73, v73, 0
	v_mfma_f32_16x16x32_f16 v[56:59], v[4:7], v[44:47], v[56:59]
	v_pk_max_f16 v72, v72, 0
	v_mfma_f32_16x16x32_f16 v[60:63], v[12:15], v[44:47], v[60:63]
	s_nop 3
	s_nop 1
	v_mfma_f32_16x16x32_f16 v[76:79], v[84:87], v[72:75], v[88:91]
	ds_read_b128 v[40:43], v118 offset:6144
	ds_read_b128 v[44:47], v119 offset:6144
	s_waitcnt lgkmcnt(2)
	v_mfma_f32_16x16x32_f16 v[64:67], v[0:3], v[32:35], 0
	v_cvt_pkrtz_f16_f32 v75, v62, v63
	v_cvt_pkrtz_f16_f32 v74, v60, v61
	v_pk_max_f16 v75, v75, 0
	v_pk_max_f16 v74, v74, 0
	v_mfma_f32_16x16x32_f16 v[68:71], v[8:11], v[32:35], 0
	v_cvt_pkrtz_f16_f32 v73, v58, v59
	v_cvt_pkrtz_f16_f32 v72, v56, v57
	v_pk_max_f16 v73, v73, 0
	v_mfma_f32_16x16x32_f16 v[64:67], v[4:7], v[36:39], v[64:67]
	v_pk_max_f16 v72, v72, 0
	v_cmp_le_f32_e64 s[62:63], v94, v76
	v_cmp_le_f32_e32 vcc, v95, v76
	v_mfma_f32_16x16x32_f16 v[68:71], v[12:15], v[36:39], v[68:71]
	s_nop 1
	v_mfma_f32_16x16x32_f16 v[80:83], v[84:87], v[72:75], v[88:91]
	s_andn2_b64 s[62:63], s[62:63], vcc
	v_addc_co_u32_e32 v92, vcc, v92, v92, vcc
	s_cmp_lg_u64 s[62:63], 0
	s_cbranch_scc1 .Lp2i_slow0
.Lp2i_back0:
	ds_read_b128 v[32:35], v118 offset:8192
	ds_read_b128 v[36:39], v119 offset:8192
	s_waitcnt lgkmcnt(2)
	v_mfma_f32_16x16x32_f16 v[48:51], v[0:3], v[40:43], 0
	v_cvt_pkrtz_f16_f32 v75, v70, v71
	v_cvt_pkrtz_f16_f32 v74, v68, v69
	v_pk_max_f16 v75, v75, 0
	v_pk_max_f16 v74, v74, 0
	v_mfma_f32_16x16x32_f16 v[52:55], v[8:11], v[40:43], 0
	v_cvt_pkrtz_f16_f32 v73, v66, v67
	v_cvt_pkrtz_f16_f32 v72, v64, v65
	v_pk_max_f16 v73, v73, 0
	v_mfma_f32_16x16x32_f16 v[48:51], v[4:7], v[44:47], v[48:51]
	v_pk_max_f16 v72, v72, 0
	v_cmp_le_f32_e64 s[62:63], v94, v80
	v_cmp_le_f32_e32 vcc, v95, v80
	v_mfma_f32_16x16x32_f16 v[52:55], v[12:15], v[44:47], v[52:55]
	s_nop 1
	v_mfma_f32_16x16x32_f16 v[76:79], v[84:87], v[72:75], v[88:91]
	s_andn2_b64 s[62:63], s[62:63], vcc
	v_addc_co_u32_e32 v92, vcc, v92, v92, vcc
	s_cmp_lg_u64 s[62:63], 0
	s_cbranch_scc1 .Lp2i_slow1
.Lp2i_back1:
	ds_read_b128 v[40:43], v118 offset:10240
	ds_read_b128 v[44:47], v119 offset:10240
	s_waitcnt lgkmcnt(2)
	v_mfma_f32_16x16x32_f16 v[56:59], v[0:3], v[32:35], 0
	v_cvt_pkrtz_f16_f32 v75, v54, v55
	v_cvt_pkrtz_f16_f32 v74, v52, v53
	v_pk_max_f16 v75, v75, 0
	v_pk_max_f16 v74, v74, 0
	v_mfma_f32_16x16x32_f16 v[60:63], v[8:11], v[32:35], 0
	v_cvt_pkrtz_f16_f32 v73, v50, v51
	v_cvt_pkrtz_f16_f32 v72, v48, v49
	v_pk_max_f16 v73, v73, 0
	v_mfma_f32_16x16x32_f16 v[56:59], v[4:7], v[36:39], v[56:59]
	v_pk_max_f16 v72, v72, 0
	v_cmp_le_f32_e64 s[62:63], v94, v76
	v_cmp_le_f32_e32 vcc, v95, v76
	v_mfma_f32_16x16x32_f16 v[60:63], v[12:15], v[36:39], v[60:63]
	s_nop 1
	v_mfma_f32_16x16x32_f16 v[80:83], v[84:87], v[72:75], v[88:91]
	s_andn2_b64 s[62:63], s[62:63], vcc
	v_addc_co_u32_e32 v92, vcc, v92, v92, vcc
	s_cmp_lg_u64 s[62:63], 0
	s_cbranch_scc1 .Lp2i_slow2
.Lp2i_back2:
	ds_read_b128 v[32:35], v118 offset:12288
	ds_read_b128 v[36:39], v119 offset:12288
	s_waitcnt lgkmcnt(2)
	v_mfma_f32_16x16x32_f16 v[64:67], v[0:3], v[40:43], 0
	v_cvt_pkrtz_f16_f32 v75, v62, v63
	v_cvt_pkrtz_f16_f32 v74, v60, v61
	v_pk_max_f16 v75, v75, 0
	v_pk_max_f16 v74, v74, 0
	v_mfma_f32_16x16x32_f16 v[68:71], v[8:11], v[40:43], 0
	v_cvt_pkrtz_f16_f32 v73, v58, v59
	v_cvt_pkrtz_f16_f32 v72, v56, v57
	v_pk_max_f16 v73, v73, 0
	v_mfma_f32_16x16x32_f16 v[64:67], v[4:7], v[44:47], v[64:67]
	v_pk_max_f16 v72, v72, 0
	v_cmp_le_f32_e64 s[62:63], v94, v80
	v_cmp_le_f32_e32 vcc, v95, v80
	v_mfma_f32_16x16x32_f16 v[68:71], v[12:15], v[44:47], v[68:71]
	s_nop 1
	v_mfma_f32_16x16x32_f16 v[76:79], v[84:87], v[72:75], v[88:91]
	s_andn2_b64 s[62:63], s[62:63], vcc
	v_addc_co_u32_e32 v92, vcc, v92, v92, vcc
	s_cmp_lg_u64 s[62:63], 0
	s_cbranch_scc1 .Lp2i_slow3
.Lp2i_back3:
	ds_read_b128 v[40:43], v118 offset:14336
	ds_read_b128 v[44:47], v119 offset:14336
	s_waitcnt lgkmcnt(2)
	v_mfma_f32_16x16x32_f16 v[48:51], v[0:3], v[32:35], 0
	v_cvt_pkrtz_f16_f32 v75, v70, v71
	v_cvt_pkrtz_f16_f32 v74, v68, v69
	v_pk_max_f16 v75, v75, 0
	v_pk_max_f16 v74, v74, 0
	v_mfma_f32_16x16x32_f16 v[52:55], v[8:11], v[32:35], 0
	v_cvt_pkrtz_f16_f32 v73, v66, v67
	v_cvt_pkrtz_f16_f32 v72, v64, v65
	v_pk_max_f16 v73, v73, 0
	v_mfma_f32_16x16x32_f16 v[48:51], v[4:7], v[36:39], v[48:51]
	v_pk_max_f16 v72, v72, 0
	v_cmp_le_f32_e64 s[62:63], v94, v76
	v_cmp_le_f32_e32 vcc, v95, v76
	v_mfma_f32_16x16x32_f16 v[52:55], v[12:15], v[36:39], v[52:55]
	s_nop 1
	v_mfma_f32_16x16x32_f16 v[80:83], v[84:87], v[72:75], v[88:91]
	s_andn2_b64 s[62:63], s[62:63], vcc
	v_addc_co_u32_e32 v92, vcc, v92, v92, vcc
	s_cmp_lg_u64 s[62:63], 0
	s_cbranch_scc1 .Lp2i_slow4
; template <int PASS> ...
;     ...
;         for (int e = 0; e < 8; ++e) { const int T = Tbase + hb * 8 + e;
;             f32x4 a0 = (f32x4){0.f, 0.f, 0.f, 0.f}, a1 = a0;
;             a0 = __builtin_amdgcn_mfma_f32_16x16x32_f16(aq[0][0], kf[e][0], a0, 0, 0, 0); a0 = __builtin_amdgcn_mfma_f32_16x16x32_f16(aq[0][1], kf[e][1], a0, 0, 0, 0);
;             a1 = __builtin_amdgcn_mfma_f32_16x16x32_f16(aq[1][0], kf[e][0], a1, 0, 0, 0); a1 = __builtin_amdgcn_mfma_f32_16x16x32_f16(aq[1][1], kf[e][1], a1, 0, 0, 0);
;             const h16x2 z2 = (h16x2){(h16)0.f, (h16)0.f};
;             const h16x2 r0 = __builtin_elementwise_max(__builtin_bit_cast(h16x2, __builtin_amdgcn_cvt_pkrtz(a0[0], a0[1])), z2), r1 = __builtin_elementwise_max(__builtin_bit_cast(h16x2, __builtin_amdgcn_cvt_pkrtz(a0[2], a0[3])), z2);
;             const h16x2 r2 = __builtin_elementwise_max(__builtin_bit_cast(h16x2, __builtin_amdgcn_cvt_pkrtz(a1[0], a1[1])), z2), r3 = __builtin_elementwise_max(__builtin_bit_cast(h16x2, __builtin_amdgcn_cvt_pkrtz(a1[2], a1[3])), z2);
;             const float sa = __builtin_amdgcn_fdot2(r0, wp[0], __builtin_amdgcn_fdot2(r1, wp[1], __builtin_amdgcn_fdot2(r2, wp[2], __builtin_amdgcn_fdot2(r3, wp[3], 0.f, false), false), false), false);
;             const int key = 16 * T + fr;
;             if (key <= tq) {
;                 const unsigned bin = (unsigned)(int)fminf(fmaxf(sa * 32.f + 128.f, 0.f), 255.f);
;                 if (PASS == 1) { if (bin >= b0) atomicAdd(&myhist[fq * 256 + bin], 1u); }
;                 else {
;                     if (bin > b0) { const unsigned pos = atomicAdd(&myctl[fq * 4 + 2], 1u); ((unsigned short*)myhist)[fq * 256 + (pos & 255u)] = (unsigned short)key; }
;                     else if (bin == b0) { const unsigned c = atomicAdd(&myctl[fq * 4 + 3], 1u);
;                         if (c < 128u) { float s = 0.f;
; #pragma unroll
;                             for (int r = 0; r < 4; ++r) s += wv[r] * fmaxf(a0[r], 0.f) + wv[4 + r] * fmaxf(a1[r], 0.f);
;                             s = fminf(fmaxf(s, -3.99f), 3.99f);
;                             mycand[(fq * 128 + c) * 2] = (unsigned)((s + 4.f) * 536870912.f); mycand[(fq * 128 + c) * 2 + 1] = (unsigned)key; } }
;                 }
.Lp2i_back4:
	ds_read_b128 v[32:35], v118 offset:16384
	ds_read_b128 v[36:39], v119 offset:16384
	s_waitcnt lgkmcnt(2)
	v_mfma_f32_16x16x32_f16 v[56:59], v[0:3], v[40:43], 0
	v_cvt_pkrtz_f16_f32 v75, v54, v55
	v_cvt_pkrtz_f16_f32 v74, v52, v53
	v_pk_max_f16 v75, v75, 0
	v_pk_max_f16 v74, v74, 0
	v_mfma_f32_16x16x32_f16 v[60:63], v[8:11], v[40:43], 0
	v_cvt_pkrtz_f16_f32 v73, v50, v51
	v_cvt_pkrtz_f16_f32 v72, v48, v49
	v_pk_max_f16 v73, v73, 0
	v_mfma_f32_16x16x32_f16 v[56:59], v[4:7], v[44:47], v[56:59]
	v_pk_max_f16 v72, v72, 0
	v_cmp_le_f32_e64 s[62:63], v94, v80
	v_cmp_le_f32_e32 vcc, v95, v80
	v_mfma_f32_16x16x32_f16 v[60:63], v[12:15], v[44:47], v[60:63]
	s_nop 1
	v_mfma_f32_16x16x32_f16 v[76:79], v[84:87], v[72:75], v[88:91]
	s_andn2_b64 s[62:63], s[62:63], vcc
	v_addc_co_u32_e32 v92, vcc, v92, v92, vcc
	s_cmp_lg_u64 s[62:63], 0
	s_cbranch_scc1 .Lp2i_slow5
.Lp2i_back5:
	ds_read_b128 v[40:43], v118 offset:18432
	ds_read_b128 v[44:47], v119 offset:18432
	s_waitcnt lgkmcnt(2)
	v_mfma_f32_16x16x32_f16 v[64:67], v[0:3], v[32:35], 0
	v_cvt_pkrtz_f16_f32 v75, v62, v63
	v_cvt_pkrtz_f16_f32 v74, v60, v61
	v_pk_max_f16 v75, v75, 0
	v_pk_max_f16 v74, v74, 0
	v_mfma_f32_16x16x32_f16 v[68:71], v[8:11], v[32:35], 0
	v_cvt_pkrtz_f16_f32 v73, v58, v59
	v_cvt_pkrtz_f16_f32 v72, v56, v57
	v_pk_max_f16 v73, v73, 0
	v_mfma_f32_16x16x32_f16 v[64:67], v[4:7], v[36:39], v[64:67]
	v_pk_max_f16 v72, v72, 0
	v_cmp_le_f32_e64 s[62:63], v94, v76
	v_cmp_le_f32_e32 vcc, v95, v76
	v_mfma_f32_16x16x32_f16 v[68:71], v[12:15], v[36:39], v[68:71]
	s_nop 1
	v_mfma_f32_16x16x32_f16 v[80:83], v[84:87], v[72:75], v[88:91]
	s_andn2_b64 s[62:63], s[62:63], vcc
	v_addc_co_u32_e32 v92, vcc, v92, v92, vcc
	s_cmp_lg_u64 s[62:63], 0
	s_cbranch_scc1 .Lp2i_slow6
.Lp2i_back6:
	ds_read_b128 v[32:35], v118 offset:20480
	ds_read_b128 v[36:39], v119 offset:20480
	s_waitcnt lgkmcnt(2)
	v_mfma_f32_16x16x32_f16 v[48:51], v[0:3], v[40:43], 0
	v_cvt_pkrtz_f16_f32 v75, v70, v71
	v_cvt_pkrtz_f16_f32 v74, v68, v69
	v_pk_max_f16 v75, v75, 0
	v_pk_max_f16 v74, v74, 0
	v_mfma_f32_16x16x32_f16 v[52:55], v[8:11], v[40:43], 0
	v_cvt_pkrtz_f16_f32 v73, v66, v67
	v_cvt_pkrtz_f16_f32 v72, v64, v65
	v_pk_max_f16 v73, v73, 0
	v_mfma_f32_16x16x32_f16 v[48:51], v[4:7], v[44:47], v[48:51]
	v_pk_max_f16 v72, v72, 0
	v_cmp_le_f32_e64 s[62:63], v94, v80
	v_cmp_le_f32_e32 vcc, v95, v80
	v_mfma_f32_16x16x32_f16 v[52:55], v[12:15], v[44:47], v[52:55]
	s_nop 1
	v_mfma_f32_16x16x32_f16 v[76:79], v[84:87], v[72:75], v[88:91]
	s_andn2_b64 s[62:63], s[62:63], vcc
	v_addc_co_u32_e32 v92, vcc, v92, v92, vcc
	s_cmp_lg_u64 s[62:63], 0
	s_cbranch_scc1 .Lp2i_slow7
.Lp2i_back7:
	ds_read_b128 v[40:43], v118 offset:22528
	ds_read_b128 v[44:47], v119 offset:22528
	s_waitcnt lgkmcnt(2)
	v_mfma_f32_16x16x32_f16 v[56:59], v[0:3], v[32:35], 0
	v_cvt_pkrtz_f16_f32 v75, v54, v55
	v_cvt_pkrtz_f16_f32 v74, v52, v53
	v_pk_max_f16 v75, v75, 0
	v_pk_max_f16 v74, v74, 0
	v_mfma_f32_16x16x32_f16 v[60:63], v[8:11], v[32:35], 0
	v_cvt_pkrtz_f16_f32 v73, v50, v51
	v_cvt_pkrtz_f16_f32 v72, v48, v49
	v_pk_max_f16 v73, v73, 0
	v_mfma_f32_16x16x32_f16 v[56:59], v[4:7], v[36:39], v[56:59]
	v_pk_max_f16 v72, v72, 0
	v_cmp_le_f32_e64 s[62:63], v94, v76
	v_cmp_le_f32_e32 vcc, v95, v76
	v_mfma_f32_16x16x32_f16 v[60:63], v[12:15], v[36:39], v[60:63]
	s_nop 1
	v_mfma_f32_16x16x32_f16 v[80:83], v[84:87], v[72:75], v[88:91]
	s_andn2_b64 s[62:63], s[62:63], vcc
	v_addc_co_u32_e32 v92, vcc, v92, v92, vcc
	s_cmp_lg_u64 s[62:63], 0
	s_cbranch_scc1 .Lp2i_slow8
.Lp2i_back8:
	ds_read_b128 v[32:35], v118 offset:24576
	ds_read_b128 v[36:39], v119 offset:24576
	s_waitcnt lgkmcnt(2)
	v_mfma_f32_16x16x32_f16 v[64:67], v[0:3], v[40:43], 0
	v_cvt_pkrtz_f16_f32 v75, v62, v63
	v_cvt_pkrtz_f16_f32 v74, v60, v61
	v_pk_max_f16 v75, v75, 0
	v_pk_max_f16 v74, v74, 0
	v_mfma_f32_16x16x32_f16 v[68:71], v[8:11], v[40:43], 0
	v_cvt_pkrtz_f16_f32 v73, v58, v59
	v_cvt_pkrtz_f16_f32 v72, v56, v57
	v_pk_max_f16 v73, v73, 0
	v_mfma_f32_16x16x32_f16 v[64:67], v[4:7], v[44:47], v[64:67]
	v_pk_max_f16 v72, v72, 0
	v_cmp_le_f32_e64 s[62:63], v94, v80
	v_cmp_le_f32_e32 vcc, v95, v80
	v_mfma_f32_16x16x32_f16 v[68:71], v[12:15], v[44:47], v[68:71]
	s_nop 1
	v_mfma_f32_16x16x32_f16 v[76:79], v[84:87], v[72:75], v[88:91]
	s_andn2_b64 s[62:63], s[62:63], vcc
	v_addc_co_u32_e32 v92, vcc, v92, v92, vcc
	s_cmp_lg_u64 s[62:63], 0
	s_cbranch_scc1 .Lp2i_slow9
; template <int PASS> ...
;     ...
;         for (int e = 0; e < 8; ++e) { const int T = Tbase + hb * 8 + e;
;             f32x4 a0 = (f32x4){0.f, 0.f, 0.f, 0.f}, a1 = a0;
;             a0 = __builtin_amdgcn_mfma_f32_16x16x32_f16(aq[0][0], kf[e][0], a0, 0, 0, 0); a0 = __builtin_amdgcn_mfma_f32_16x16x32_f16(aq[0][1], kf[e][1], a0, 0, 0, 0);
;             a1 = __builtin_amdgcn_mfma_f32_16x16x32_f16(aq[1][0], kf[e][0], a1, 0, 0, 0); a1 = __builtin_amdgcn_mfma_f32_16x16x32_f16(aq[1][1], kf[e][1], a1, 0, 0, 0);
;             const h16x2 z2 = (h16x2){(h16)0.f, (h16)0.f};
;             const h16x2 r0 = __builtin_elementwise_max(__builtin_bit_cast(h16x2, __builtin_amdgcn_cvt_pkrtz(a0[0], a0[1])), z2), r1 = __builtin_elementwise_max(__builtin_bit_cast(h16x2, __builtin_amdgcn_cvt_pkrtz(a0[2], a0[3])), z2);
;             const h16x2 r2 = __builtin_elementwise_max(__builtin_bit_cast(h16x2, __builtin_amdgcn_cvt_pkrtz(a1[0], a1[1])), z2), r3 = __builtin_elementwise_max(__builtin_bit_cast(h16x2, __builtin_amdgcn_cvt_pkrtz(a1[2], a1[3])), z2);
;             const float sa = __builtin_amdgcn_fdot2(r0, wp[0], __builtin_amdgcn_fdot2(r1, wp[1], __builtin_amdgcn_fdot2(r2, wp[2], __builtin_amdgcn_fdot2(r3, wp[3], 0.f, false), false), false), false);
;             const int key = 16 * T + fr;
;             if (key <= tq) {
;                 const unsigned bin = (unsigned)(int)fminf(fmaxf(sa * 32.f + 128.f, 0.f), 255.f);
;                 if (PASS == 1) { if (bin >= b0) atomicAdd(&myhist[fq * 256 + bin], 1u); }
;                 else {
;                     if (bin > b0) { const unsigned pos = atomicAdd(&myctl[fq * 4 + 2], 1u); ((unsigned short*)myhist)[fq * 256 + (pos & 255u)] = (unsigned short)key; }
;                     else if (bin == b0) { const unsigned c = atomicAdd(&myctl[fq * 4 + 3], 1u);
;                         if (c < 128u) { float s = 0.f;
; #pragma unroll
;                             for (int r = 0; r < 4; ++r) s += wv[r] * fmaxf(a0[r], 0.f) + wv[4 + r] * fmaxf(a1[r], 0.f);
;                             s = fminf(fmaxf(s, -3.99f), 3.99f);
;                             mycand[(fq * 128 + c) * 2] = (unsigned)((s + 4.f) * 536870912.f); mycand[(fq * 128 + c) * 2 + 1] = (unsigned)key; } }
;                 }
.Lp2i_back9:
	ds_read_b128 v[40:43], v118 offset:26624
	ds_read_b128 v[44:47], v119 offset:26624
	s_waitcnt lgkmcnt(2)
	v_mfma_f32_16x16x32_f16 v[48:51], v[0:3], v[32:35], 0
	v_cvt_pkrtz_f16_f32 v75, v70, v71
	v_cvt_pkrtz_f16_f32 v74, v68, v69
	v_pk_max_f16 v75, v75, 0
	v_pk_max_f16 v74, v74, 0
	v_mfma_f32_16x16x32_f16 v[52:55], v[8:11], v[32:35], 0
	v_cvt_pkrtz_f16_f32 v73, v66, v67
	v_cvt_pkrtz_f16_f32 v72, v64, v65
	v_pk_max_f16 v73, v73, 0
	v_mfma_f32_16x16x32_f16 v[48:51], v[4:7], v[36:39], v[48:51]
	v_pk_max_f16 v72, v72, 0
	v_cmp_le_f32_e64 s[62:63], v94, v76
	v_cmp_le_f32_e32 vcc, v95, v76
	v_mfma_f32_16x16x32_f16 v[52:55], v[12:15], v[36:39], v[52:55]
	s_nop 1
	v_mfma_f32_16x16x32_f16 v[80:83], v[84:87], v[72:75], v[88:91]
	s_andn2_b64 s[62:63], s[62:63], vcc
	v_addc_co_u32_e32 v92, vcc, v92, v92, vcc
	s_cmp_lg_u64 s[62:63], 0
	s_cbranch_scc1 .Lp2i_slow10
.Lp2i_back10:
	ds_read_b128 v[32:35], v118 offset:28672
	ds_read_b128 v[36:39], v119 offset:28672
	s_waitcnt lgkmcnt(2)
	v_mfma_f32_16x16x32_f16 v[56:59], v[0:3], v[40:43], 0
	v_cvt_pkrtz_f16_f32 v75, v54, v55
	v_cvt_pkrtz_f16_f32 v74, v52, v53
	v_pk_max_f16 v75, v75, 0
	v_pk_max_f16 v74, v74, 0
	v_mfma_f32_16x16x32_f16 v[60:63], v[8:11], v[40:43], 0
	v_cvt_pkrtz_f16_f32 v73, v50, v51
	v_cvt_pkrtz_f16_f32 v72, v48, v49
	v_pk_max_f16 v73, v73, 0
	v_mfma_f32_16x16x32_f16 v[56:59], v[4:7], v[44:47], v[56:59]
	v_pk_max_f16 v72, v72, 0
	v_cmp_le_f32_e64 s[62:63], v94, v80
	v_cmp_le_f32_e32 vcc, v95, v80
	v_mfma_f32_16x16x32_f16 v[60:63], v[12:15], v[44:47], v[60:63]
	s_nop 1
	v_mfma_f32_16x16x32_f16 v[76:79], v[84:87], v[72:75], v[88:91]
	s_andn2_b64 s[62:63], s[62:63], vcc
	v_addc_co_u32_e32 v92, vcc, v92, v92, vcc
	s_cmp_lg_u64 s[62:63], 0
	s_cbranch_scc1 .Lp2i_slow11
.Lp2i_back11:
	ds_read_b128 v[40:43], v118 offset:30720
	ds_read_b128 v[44:47], v119 offset:30720
	s_waitcnt lgkmcnt(2)
	v_mfma_f32_16x16x32_f16 v[64:67], v[0:3], v[32:35], 0
	v_cvt_pkrtz_f16_f32 v75, v62, v63
	v_cvt_pkrtz_f16_f32 v74, v60, v61
	v_pk_max_f16 v75, v75, 0
	v_pk_max_f16 v74, v74, 0
	v_mfma_f32_16x16x32_f16 v[68:71], v[8:11], v[32:35], 0
	v_cvt_pkrtz_f16_f32 v73, v58, v59
	v_cvt_pkrtz_f16_f32 v72, v56, v57
	v_pk_max_f16 v73, v73, 0
	v_mfma_f32_16x16x32_f16 v[64:67], v[4:7], v[36:39], v[64:67]
	v_pk_max_f16 v72, v72, 0
	v_cmp_le_f32_e64 s[62:63], v94, v76
	v_cmp_le_f32_e32 vcc, v95, v76
	v_mfma_f32_16x16x32_f16 v[68:71], v[12:15], v[36:39], v[68:71]
	s_nop 1
	v_mfma_f32_16x16x32_f16 v[80:83], v[84:87], v[72:75], v[88:91]
	s_andn2_b64 s[62:63], s[62:63], vcc
	v_addc_co_u32_e32 v92, vcc, v92, v92, vcc
	s_cmp_lg_u64 s[62:63], 0
	s_cbranch_scc1 .Lp2i_slow12
.Lp2i_back12:
	s_nop 3
	s_waitcnt lgkmcnt(0)
	v_mfma_f32_16x16x32_f16 v[48:51], v[0:3], v[40:43], 0
	v_cvt_pkrtz_f16_f32 v75, v70, v71
	v_cvt_pkrtz_f16_f32 v74, v68, v69
	v_pk_max_f16 v75, v75, 0
	v_pk_max_f16 v74, v74, 0
	v_mfma_f32_16x16x32_f16 v[52:55], v[8:11], v[40:43], 0
	v_cvt_pkrtz_f16_f32 v73, v66, v67
	v_cvt_pkrtz_f16_f32 v72, v64, v65
	v_pk_max_f16 v73, v73, 0
	v_mfma_f32_16x16x32_f16 v[48:51], v[4:7], v[44:47], v[48:51]
	v_pk_max_f16 v72, v72, 0
	v_cmp_le_f32_e64 s[62:63], v94, v80
	v_cmp_le_f32_e32 vcc, v95, v80
	v_mfma_f32_16x16x32_f16 v[52:55], v[12:15], v[44:47], v[52:55]
	s_nop 1
	v_mfma_f32_16x16x32_f16 v[76:79], v[84:87], v[72:75], v[88:91]
	s_andn2_b64 s[62:63], s[62:63], vcc
	v_addc_co_u32_e32 v92, vcc, v92, v92, vcc
	s_cmp_lg_u64 s[62:63], 0
	s_cbranch_scc1 .Lp2i_slow13
.Lp2i_back13:
	s_nop 3
	v_cvt_pkrtz_f16_f32 v75, v54, v55
	v_cvt_pkrtz_f16_f32 v74, v52, v53
	v_pk_max_f16 v75, v75, 0
	v_pk_max_f16 v74, v74, 0
	v_cvt_pkrtz_f16_f32 v73, v50, v51
	v_cvt_pkrtz_f16_f32 v72, v48, v49
	v_pk_max_f16 v73, v73, 0
	v_pk_max_f16 v72, v72, 0
	v_cmp_le_f32_e64 s[62:63], v94, v76
	v_cmp_le_f32_e32 vcc, v95, v76
	s_nop 1
	v_mfma_f32_16x16x32_f16 v[80:83], v[84:87], v[72:75], v[88:91]
	s_andn2_b64 s[62:63], s[62:63], vcc
	v_addc_co_u32_e32 v92, vcc, v92, v92, vcc
	s_cmp_lg_u64 s[62:63], 0
	s_cbranch_scc1 .Lp2i_slow14
.Lp2i_back14:
	s_nop 7
	s_nop 3
	v_cmp_le_f32_e64 s[62:63], v94, v80
	v_cmp_le_f32_e32 vcc, v95, v80
	s_andn2_b64 s[62:63], s[62:63], vcc
	v_addc_co_u32_e32 v92, vcc, v92, v92, vcc
	s_cmp_lg_u64 s[62:63], 0
	s_cbranch_scc1 .Lp2i_slow15

; __device__ __forceinline__ void dsa_attend(const h16* PROJ, const unsigned short* IDX, const int* CNT, h16* MIXA, unsigned char* shm, unsigned* bar, unsigned xcc, unsigned xrank) {
;     ...
;             if (fr < 4) { const h16* qrow = PROJ + O_Q + (size_t)tokq * 1024 + (g * 4 + fr) * 128 + 16 * fq;
; #pragma unroll
;                 for (int kk = 0; kk < 4; ++kk) qa[kk] = *(const h16x8*)(qrow + (kk & 1) * 8 + (kk >> 1) * 64); }
;             long qa8[4];
; #pragma unroll
;             for (int kk = 0; kk < 4; ++kk) {
;                 int w0 = __builtin_amdgcn_cvt_pk_fp8_f32((float)qa[kk][0], (float)qa[kk][1], 0, false); w0 = __builtin_amdgcn_cvt_pk_fp8_f32((float)qa[kk][2], (float)qa[kk][3], w0, true);
;                 int w1 = __builtin_amdgcn_cvt_pk_fp8_f32((float)qa[kk][4], (float)qa[kk][5], 0, false); w1 = __builtin_amdgcn_cvt_pk_fp8_f32((float)qa[kk][6], (float)qa[kk][7], w1, true);
;                 qa8[kk] = (long)(((unsigned long long)(unsigned)w1 << 32) | (unsigned long long)(unsigned)w0); }
;             f32x4 sacc[16];
;             const unsigned char* kbase8 = (const unsigned char*)(PROJ + O_KG) + (size_t)(b * 2 + g) * SEQ * 128 + 16 * fq;
;             {
;                 uint4 kf[16][2];
; #pragma unroll
;                 for (int e = 0; e < 16; ++e) { const int slot = 16 * e + fr; const int idx = (int)sel[qq * 256 + (slot < nsel ? slot : nsel - 1)];
;                     const unsigned char* krow = kbase8 + (size_t)idx * 128;
;                     kf[e][0] = *(const uint4*)krow; kf[e][1] = *(const uint4*)(krow + 64); }
.LBB0_846:
	s_or_b64 exec, exec, s[50:51]
	s_waitcnt vmcnt(3)
	v_cvt_f32_f16_e32 v16, v12
	v_cvt_f32_f16_sdwa v12, v12 dst_sel:DWORD dst_unused:UNUSED_PAD src0_sel:WORD_1
	v_mov_b32_e32 v148, v163
	v_mov_b32_e32 v149, v163
	v_mov_b32_e32 v150, v163
	v_cvt_pk_fp8_f32 v148, v16, v12
	v_cvt_f32_f16_e32 v12, v13
	v_cvt_f32_f16_sdwa v13, v13 dst_sel:DWORD dst_unused:UNUSED_PAD src0_sel:WORD_1
	v_mov_b32_e32 v151, v163
	v_mov_b32_e32 v152, v163
	v_mov_b32_e32 v153, v163
	v_cvt_pk_fp8_f32 v148, v12, v13 op_sel:[0,0,1]
	v_cvt_f32_f16_e32 v12, v14
	v_cvt_f32_f16_sdwa v13, v14 dst_sel:DWORD dst_unused:UNUSED_PAD src0_sel:WORD_1
	v_mov_b32_e32 v154, v163
	v_mov_b32_e32 v155, v163
	s_max_i32 s50, s67, 1
	v_cvt_pk_fp8_f32 v149, v12, v13
	v_cvt_f32_f16_e32 v12, v15
	v_cvt_f32_f16_sdwa v13, v15 dst_sel:DWORD dst_unused:UNUSED_PAD src0_sel:WORD_1
	s_min_i32 s67, s50, 0x100
	s_add_i32 s70, s67, -1
	v_min_u32_e32 v16, s70, v195
	v_cvt_pk_fp8_f32 v149, v12, v13 op_sel:[0,0,1]
	s_waitcnt vmcnt(2)
	v_cvt_f32_f16_e32 v12, v8
	v_cvt_f32_f16_sdwa v8, v8 dst_sel:DWORD dst_unused:UNUSED_PAD src0_sel:WORD_1
	v_lshl_add_u32 v16, v16, 1, v190
	v_min_u32_e32 v24, s70, v196
	v_lshl_add_u32 v24, v24, 1, v190
	v_cvt_pk_fp8_f32 v150, v12, v8
	v_cvt_f32_f16_e32 v8, v9
	v_cvt_f32_f16_sdwa v9, v9 dst_sel:DWORD dst_unused:UNUSED_PAD src0_sel:WORD_1
	v_min_u32_e32 v32, s70, v197
	v_lshl_add_u32 v32, v32, 1, v190
	v_min_u32_e32 v40, s70, v198
	v_cvt_pk_fp8_f32 v150, v8, v9 op_sel:[0,0,1]
	v_cvt_f32_f16_e32 v8, v10
	v_cvt_f32_f16_sdwa v9, v10 dst_sel:DWORD dst_unused:UNUSED_PAD src0_sel:WORD_1
	v_lshl_add_u32 v40, v40, 1, v190
	v_min_u32_e32 v48, s70, v199
	v_lshl_add_u32 v48, v48, 1, v190
	v_cvt_pk_fp8_f32 v151, v8, v9
	v_cvt_f32_f16_e32 v8, v11
	v_cvt_f32_f16_sdwa v9, v11 dst_sel:DWORD dst_unused:UNUSED_PAD src0_sel:WORD_1
	v_min_u32_e32 v56, s70, v200
	v_lshl_add_u32 v56, v56, 1, v190
	s_waitcnt lgkmcnt(8)
	v_min_u32_e32 v64, s70, v201
	v_cvt_pk_fp8_f32 v151, v8, v9 op_sel:[0,0,1]
	s_waitcnt vmcnt(1)
	v_cvt_f32_f16_e32 v8, v0
	v_cvt_f32_f16_sdwa v0, v0 dst_sel:DWORD dst_unused:UNUSED_PAD src0_sel:WORD_1
	v_lshl_add_u32 v64, v64, 1, v190
	v_min_u32_e32 v72, s70, v202
	v_lshl_add_u32 v72, v72, 1, v190
	v_cvt_pk_fp8_f32 v152, v8, v0
	v_cvt_f32_f16_e32 v0, v1
	v_cvt_f32_f16_sdwa v1, v1 dst_sel:DWORD dst_unused:UNUSED_PAD src0_sel:WORD_1
	v_min_u32_e32 v8, s70, v194
	v_lshl_add_u32 v8, v8, 1, v190
	v_min_u32_e32 v80, s70, v203
	v_cvt_pk_fp8_f32 v152, v0, v1 op_sel:[0,0,1]
	v_cvt_f32_f16_e32 v0, v2
	v_cvt_f32_f16_sdwa v1, v2 dst_sel:DWORD dst_unused:UNUSED_PAD src0_sel:WORD_1
	v_lshl_add_u32 v80, v80, 1, v190
	v_min_u32_e32 v84, s70, v204
	v_lshl_add_u32 v84, v84, 1, v190
	v_cvt_pk_fp8_f32 v153, v0, v1
	v_cvt_f32_f16_e32 v0, v3
	v_cvt_f32_f16_sdwa v1, v3 dst_sel:DWORD dst_unused:UNUSED_PAD src0_sel:WORD_1
	v_min_u32_e32 v92, s70, v205
	v_lshl_add_u32 v92, v92, 1, v190
	v_min_u32_e32 v100, s70, v206
	v_cvt_pk_fp8_f32 v153, v0, v1 op_sel:[0,0,1]
	s_waitcnt vmcnt(0)
	v_cvt_f32_f16_e32 v0, v4
	v_cvt_f32_f16_sdwa v1, v4 dst_sel:DWORD dst_unused:UNUSED_PAD src0_sel:WORD_1
	v_lshl_add_u32 v100, v100, 1, v190
	v_min_u32_e32 v108, s70, v207
	v_lshl_add_u32 v108, v108, 1, v190
	v_cvt_pk_fp8_f32 v154, v0, v1
	v_cvt_f32_f16_e32 v0, v5
	v_cvt_f32_f16_sdwa v1, v5 dst_sel:DWORD dst_unused:UNUSED_PAD src0_sel:WORD_1
	v_min_u32_e32 v120, s70, v208
	v_lshl_add_u32 v120, v120, 1, v190
	v_cvt_pk_fp8_f32 v154, v0, v1 op_sel:[0,0,1]
	v_cvt_f32_f16_e32 v0, v6
	v_cvt_f32_f16_sdwa v1, v6 dst_sel:DWORD dst_unused:UNUSED_PAD src0_sel:WORD_1
	v_cvt_pk_fp8_f32 v155, v0, v1
	v_cvt_f32_f16_e32 v0, v7
	v_cvt_f32_f16_sdwa v1, v7 dst_sel:DWORD dst_unused:UNUSED_PAD src0_sel:WORD_1
	v_cvt_pk_fp8_f32 v155, v0, v1 op_sel:[0,0,1]
	v_min_u32_e32 v0, s70, v189
	v_lshl_add_u32 v0, v0, 1, v190
	ds_read_u16 v0, v0 offset:32768
	s_waitcnt lgkmcnt(0)
	v_lshlrev_b32_e32 v162, 7, v0
	v_lshl_add_u64 v[0:1], v[140:141], 0, v[162:163]
	global_load_dwordx4 v[4:7], v[0:1], off
	s_nop 0
	global_load_dwordx4 v[0:3], v[0:1], off offset:64
	ds_read_u16 v8, v8 offset:32768
	s_waitcnt lgkmcnt(0)
	v_lshlrev_b32_e32 v162, 7, v8
	v_lshl_add_u64 v[8:9], v[140:141], 0, v[162:163]
	global_load_dwordx4 v[12:15], v[8:9], off
	s_nop 0
	global_load_dwordx4 v[8:11], v[8:9], off offset:64
	ds_read_u16 v16, v16 offset:32768
	s_waitcnt lgkmcnt(0)
	v_lshlrev_b32_e32 v162, 7, v16
	v_lshl_add_u64 v[16:17], v[140:141], 0, v[162:163]
	global_load_dwordx4 v[20:23], v[16:17], off
	s_nop 0
	global_load_dwordx4 v[16:19], v[16:17], off offset:64
	ds_read_u16 v24, v24 offset:32768
	s_waitcnt lgkmcnt(0)
	v_lshlrev_b32_e32 v162, 7, v24
	v_lshl_add_u64 v[24:25], v[140:141], 0, v[162:163]
	global_load_dwordx4 v[28:31], v[24:25], off
	s_nop 0
	global_load_dwordx4 v[24:27], v[24:25], off offset:64
	ds_read_u16 v32, v32 offset:32768
	s_waitcnt lgkmcnt(0)
	v_lshlrev_b32_e32 v162, 7, v32
	v_lshl_add_u64 v[32:33], v[140:141], 0, v[162:163]
	global_load_dwordx4 v[36:39], v[32:33], off
	s_nop 0
	global_load_dwordx4 v[32:35], v[32:33], off offset:64
	ds_read_u16 v40, v40 offset:32768
	s_waitcnt lgkmcnt(0)
	v_lshlrev_b32_e32 v162, 7, v40
	v_lshl_add_u64 v[40:41], v[140:141], 0, v[162:163]
	global_load_dwordx4 v[44:47], v[40:41], off
	s_nop 0
	global_load_dwordx4 v[40:43], v[40:41], off offset:64
	ds_read_u16 v48, v48 offset:32768
	s_waitcnt lgkmcnt(0)
	v_lshlrev_b32_e32 v162, 7, v48
	v_lshl_add_u64 v[48:49], v[140:141], 0, v[162:163]
	global_load_dwordx4 v[52:55], v[48:49], off
	s_nop 0
	global_load_dwordx4 v[48:51], v[48:49], off offset:64
	ds_read_u16 v56, v56 offset:32768
	s_waitcnt lgkmcnt(0)
; __device__ __forceinline__ void dsa_attend(const h16* PROJ, const unsigned short* IDX, const int* CNT, h16* MIXA, unsigned char* shm, unsigned* bar, unsigned xcc, unsigned xrank) {
;     ...
;                 uint4 kf[16][2];
; #pragma unroll
;                 for (int e = 0; e < 16; ++e) { const int slot = 16 * e + fr; const int idx = (int)sel[qq * 256 + (slot < nsel ? slot : nsel - 1)];
;                     const unsigned char* krow = kbase8 + (size_t)idx * 128;
;                     kf[e][0] = *(const uint4*)krow; kf[e][1] = *(const uint4*)(krow + 64); }
;                 __builtin_amdgcn_sched_barrier(0);
; #pragma unroll
;                 for (int e = 0; e < 16; ++e) {
;                     f32x4 a = (f32x4){0.f, 0.f, 0.f, 0.f};
; #pragma unroll
;                     for (int L = 0; L < 2; ++L) {
;                         const long k0 = (long)(((unsigned long long)kf[e][L].y << 32) | (unsigned long long)kf[e][L].x), k1 = (long)(((unsigned long long)kf[e][L].w << 32) | (unsigned long long)kf[e][L].z);
;                         a = __builtin_amdgcn_mfma_f32_16x16x32_fp8_fp8(qa8[2 * L], k0, a, 0, 0, 0); a = __builtin_amdgcn_mfma_f32_16x16x32_fp8_fp8(qa8[2 * L + 1], k1, a, 0, 0, 0); }
;                     if (16 * e + fr >= nsel) a = (f32x4){-1e30f, -1e30f, -1e30f, -1e30f};
;                     sacc[e] = a; }
;                 __builtin_amdgcn_sched_barrier(0);
	v_lshlrev_b32_e32 v162, 7, v56
	v_lshl_add_u64 v[56:57], v[140:141], 0, v[162:163]
	global_load_dwordx4 v[60:63], v[56:57], off
	s_nop 0
	global_load_dwordx4 v[56:59], v[56:57], off offset:64
	ds_read_u16 v64, v64 offset:32768
	s_waitcnt lgkmcnt(0)
	v_lshlrev_b32_e32 v162, 7, v64
	v_lshl_add_u64 v[64:65], v[140:141], 0, v[162:163]
	global_load_dwordx4 v[68:71], v[64:65], off
	s_nop 0
	global_load_dwordx4 v[64:67], v[64:65], off offset:64
	ds_read_u16 v72, v72 offset:32768
	s_waitcnt lgkmcnt(0)
	v_lshlrev_b32_e32 v162, 7, v72
	v_lshl_add_u64 v[72:73], v[140:141], 0, v[162:163]
	global_load_dwordx4 v[76:79], v[72:73], off
	s_nop 0
	global_load_dwordx4 v[72:75], v[72:73], off offset:64
	ds_read_u16 v80, v80 offset:32768
	s_waitcnt lgkmcnt(0)
	v_lshlrev_b32_e32 v162, 7, v80
	v_lshl_add_u64 v[80:81], v[140:141], 0, v[162:163]
	global_load_dwordx4 v[88:91], v[80:81], off
	s_nop 0
	global_load_dwordx4 v[80:83], v[80:81], off offset:64
	ds_read_u16 v84, v84 offset:32768
	s_waitcnt lgkmcnt(0)
	v_lshlrev_b32_e32 v162, 7, v84
	v_lshl_add_u64 v[84:85], v[140:141], 0, v[162:163]
	global_load_dwordx4 v[96:99], v[84:85], off
	s_nop 0
	global_load_dwordx4 v[84:87], v[84:85], off offset:64
	ds_read_u16 v92, v92 offset:32768
	s_waitcnt lgkmcnt(0)
	v_lshlrev_b32_e32 v162, 7, v92
	v_lshl_add_u64 v[92:93], v[140:141], 0, v[162:163]
	global_load_dwordx4 v[104:107], v[92:93], off
	s_nop 0
	global_load_dwordx4 v[92:95], v[92:93], off offset:64
	ds_read_u16 v100, v100 offset:32768
	s_waitcnt lgkmcnt(0)
	v_lshlrev_b32_e32 v162, 7, v100
	v_lshl_add_u64 v[100:101], v[140:141], 0, v[162:163]
	global_load_dwordx4 v[112:115], v[100:101], off
	s_nop 0
	global_load_dwordx4 v[100:103], v[100:101], off offset:64
	ds_read_u16 v108, v108 offset:32768
	s_waitcnt lgkmcnt(0)
	v_lshlrev_b32_e32 v162, 7, v108
	v_lshl_add_u64 v[108:109], v[140:141], 0, v[162:163]
	global_load_dwordx4 v[116:119], v[108:109], off
	s_nop 0
	global_load_dwordx4 v[108:111], v[108:109], off offset:64
	ds_read_u16 v120, v120 offset:32768
	s_waitcnt lgkmcnt(0)
	v_lshlrev_b32_e32 v162, 7, v120
	v_lshl_add_u64 v[120:121], v[140:141], 0, v[162:163]
	global_load_dwordx4 v[124:127], v[120:121], off
	s_nop 0
	global_load_dwordx4 v[120:123], v[120:121], off offset:64
	s_waitcnt vmcnt(31)
	v_mfma_f32_16x16x32_fp8_fp8 v[156:159], v[148:149], v[4:5], 0
	v_cmp_gt_u32_e32 vcc, s50, v189
	v_mfma_f32_16x16x32_fp8_fp8 v[4:7], v[150:151], v[6:7], v[156:159]
	s_waitcnt vmcnt(30)
	v_mfma_f32_16x16x32_fp8_fp8 v[4:7], v[152:153], v[0:1], v[4:7]
	v_mfma_f32_16x16x32_fp8_fp8 v[4:7], v[154:155], v[2:3], v[4:7]
	s_waitcnt vmcnt(29)
	v_mfma_f32_16x16x32_fp8_fp8 v[0:3], v[148:149], v[12:13], 0
	v_mfma_f32_16x16x32_fp8_fp8 v[0:3], v[150:151], v[14:15], v[0:3]
	s_waitcnt vmcnt(28)
	v_mfma_f32_16x16x32_fp8_fp8 v[0:3], v[152:153], v[8:9], v[0:3]
	v_mfma_f32_16x16x32_fp8_fp8 v[8:11], v[154:155], v[10:11], v[0:3]
	s_waitcnt vmcnt(27)
	v_mfma_f32_16x16x32_fp8_fp8 v[0:3], v[148:149], v[20:21], 0
	v_mfma_f32_16x16x32_fp8_fp8 v[0:3], v[150:151], v[22:23], v[0:3]
	s_waitcnt vmcnt(26)
	v_mfma_f32_16x16x32_fp8_fp8 v[0:3], v[152:153], v[16:17], v[0:3]
	v_mfma_f32_16x16x32_fp8_fp8 v[12:15], v[154:155], v[18:19], v[0:3]
	s_waitcnt vmcnt(25)
	v_mfma_f32_16x16x32_fp8_fp8 v[0:3], v[148:149], v[28:29], 0
	v_mfma_f32_16x16x32_fp8_fp8 v[0:3], v[150:151], v[30:31], v[0:3]
	s_waitcnt vmcnt(24)
	v_mfma_f32_16x16x32_fp8_fp8 v[0:3], v[152:153], v[24:25], v[0:3]
	v_mfma_f32_16x16x32_fp8_fp8 v[16:19], v[154:155], v[26:27], v[0:3]
	s_waitcnt vmcnt(23)
	v_mfma_f32_16x16x32_fp8_fp8 v[0:3], v[148:149], v[36:37], 0
	v_mfma_f32_16x16x32_fp8_fp8 v[0:3], v[150:151], v[38:39], v[0:3]
	s_waitcnt vmcnt(22)
	v_mfma_f32_16x16x32_fp8_fp8 v[0:3], v[152:153], v[32:33], v[0:3]
	v_mfma_f32_16x16x32_fp8_fp8 v[20:23], v[154:155], v[34:35], v[0:3]
	s_waitcnt vmcnt(21)
	v_mfma_f32_16x16x32_fp8_fp8 v[0:3], v[148:149], v[44:45], 0
	v_mfma_f32_16x16x32_fp8_fp8 v[0:3], v[150:151], v[46:47], v[0:3]
	s_waitcnt vmcnt(20)
	v_mfma_f32_16x16x32_fp8_fp8 v[0:3], v[152:153], v[40:41], v[0:3]
	v_mfma_f32_16x16x32_fp8_fp8 v[24:27], v[154:155], v[42:43], v[0:3]
	s_waitcnt vmcnt(19)
	v_mfma_f32_16x16x32_fp8_fp8 v[0:3], v[148:149], v[52:53], 0
	v_mfma_f32_16x16x32_fp8_fp8 v[0:3], v[150:151], v[54:55], v[0:3]
	s_waitcnt vmcnt(18)
	v_mfma_f32_16x16x32_fp8_fp8 v[0:3], v[152:153], v[48:49], v[0:3]
	v_mfma_f32_16x16x32_fp8_fp8 v[28:31], v[154:155], v[50:51], v[0:3]
	s_waitcnt vmcnt(17)
	v_mfma_f32_16x16x32_fp8_fp8 v[0:3], v[148:149], v[60:61], 0
	v_mfma_f32_16x16x32_fp8_fp8 v[0:3], v[150:151], v[62:63], v[0:3]
	s_waitcnt vmcnt(16)
	v_mfma_f32_16x16x32_fp8_fp8 v[0:3], v[152:153], v[56:57], v[0:3]
	v_mfma_f32_16x16x32_fp8_fp8 v[32:35], v[154:155], v[58:59], v[0:3]
	s_waitcnt vmcnt(15)
	v_mfma_f32_16x16x32_fp8_fp8 v[0:3], v[148:149], v[68:69], 0
	v_mfma_f32_16x16x32_fp8_fp8 v[0:3], v[150:151], v[70:71], v[0:3]
	s_waitcnt vmcnt(14)
	v_mfma_f32_16x16x32_fp8_fp8 v[0:3], v[152:153], v[64:65], v[0:3]
	v_mfma_f32_16x16x32_fp8_fp8 v[36:39], v[154:155], v[66:67], v[0:3]
	s_waitcnt vmcnt(13)
	v_mfma_f32_16x16x32_fp8_fp8 v[0:3], v[148:149], v[76:77], 0
	v_mfma_f32_16x16x32_fp8_fp8 v[0:3], v[150:151], v[78:79], v[0:3]
	s_waitcnt vmcnt(11)
	v_mfma_f32_16x16x32_fp8_fp8 v[44:47], v[148:149], v[88:89], 0
	s_waitcnt vmcnt(9)
	v_mfma_f32_16x16x32_fp8_fp8 v[48:51], v[148:149], v[96:97], 0
	v_mfma_f32_16x16x32_fp8_fp8 v[0:3], v[152:153], v[72:73], v[0:3]
	s_waitcnt vmcnt(7)
	v_mfma_f32_16x16x32_fp8_fp8 v[52:55], v[148:149], v[104:105], 0
	s_waitcnt vmcnt(5)
	v_mfma_f32_16x16x32_fp8_fp8 v[56:59], v[148:149], v[112:113], 0
	v_mfma_f32_16x16x32_fp8_fp8 v[44:47], v[150:151], v[90:91], v[44:47]
	s_waitcnt vmcnt(3)
; __device__ __forceinline__ void dsa_attend(const h16* PROJ, const unsigned short* IDX, const int* CNT, h16* MIXA, unsigned char* shm, unsigned* bar, unsigned xcc, unsigned xrank) {
;     ...
;                 for (int e = 0; e < 16; ++e) {
;                     f32x4 a = (f32x4){0.f, 0.f, 0.f, 0.f};
; #pragma unroll
;                     for (int L = 0; L < 2; ++L) {
;                         const long k0 = (long)(((unsigned long long)kf[e][L].y << 32) | (unsigned long long)kf[e][L].x), k1 = (long)(((unsigned long long)kf[e][L].w << 32) | (unsigned long long)kf[e][L].z);
;                         a = __builtin_amdgcn_mfma_f32_16x16x32_fp8_fp8(qa8[2 * L], k0, a, 0, 0, 0); a = __builtin_amdgcn_mfma_f32_16x16x32_fp8_fp8(qa8[2 * L + 1], k1, a, 0, 0, 0); }
;                     if (16 * e + fr >= nsel) a = (f32x4){-1e30f, -1e30f, -1e30f, -1e30f};
;                     sacc[e] = a; }
;                 __builtin_amdgcn_sched_barrier(0);
;             }
;             f32x4 mx = sacc[0];
; #pragma unroll
;             for (int jt = 1; jt < 16; ++jt)
; #pragma unroll
;                 for (int i = 0; i < 4; ++i) mx[i] = fmaxf(mx[i], sacc[jt][i]);
; #pragma unroll
;             for (int o = 1; o < 16; o <<= 1)
; #pragma unroll
;                 for (int i = 0; i < 4; ++i) mx[i] = fmaxf(mx[i], __shfl_xor(mx[i], o));
	v_mfma_f32_16x16x32_fp8_fp8 v[60:63], v[148:149], v[116:117], 0
	v_mfma_f32_16x16x32_fp8_fp8 v[48:51], v[150:151], v[98:99], v[48:51]
	v_mfma_f32_16x16x32_fp8_fp8 v[40:43], v[154:155], v[74:75], v[0:3]
	s_nop 2
	v_cndmask_b32_e32 v2, v219, v7, vcc
	v_cndmask_b32_e32 v3, v219, v6, vcc
	v_cndmask_b32_e32 v1, v219, v5, vcc
	v_cndmask_b32_e32 v0, v219, v4, vcc
	v_cmp_gt_u32_e32 vcc, s67, v194
	v_mfma_f32_16x16x32_fp8_fp8 v[52:55], v[150:151], v[106:107], v[52:55]
	s_nop 0
	v_cndmask_b32_e32 v7, v219, v11, vcc
	v_cndmask_b32_e32 v6, v219, v10, vcc
	v_cndmask_b32_e32 v9, v219, v9, vcc
	v_cndmask_b32_e32 v8, v219, v8, vcc
	v_cmp_gt_u32_e32 vcc, s67, v195
	v_mfma_f32_16x16x32_fp8_fp8 v[56:59], v[150:151], v[114:115], v[56:59]
	s_nop 0
	v_cndmask_b32_e32 v11, v219, v15, vcc
	v_cndmask_b32_e32 v10, v219, v14, vcc
	v_mfma_f32_16x16x32_fp8_fp8 v[44:47], v[152:153], v[80:81], v[44:47]
	v_cndmask_b32_e32 v69, v219, v13, vcc
	v_cndmask_b32_e32 v12, v219, v12, vcc
	v_cmp_gt_u32_e32 vcc, s67, v196
	v_mfma_f32_16x16x32_fp8_fp8 v[60:63], v[150:151], v[118:119], v[60:63]
	s_nop 0
	v_cndmask_b32_e32 v15, v219, v19, vcc
	v_cndmask_b32_e32 v14, v219, v18, vcc
	s_waitcnt vmcnt(1)
	v_mfma_f32_16x16x32_fp8_fp8 v[64:67], v[148:149], v[124:125], 0
	v_cndmask_b32_e32 v13, v219, v17, vcc
	v_cndmask_b32_e32 v70, v219, v16, vcc
	v_cmp_gt_u32_e32 vcc, s67, v197
	v_mfma_f32_16x16x32_fp8_fp8 v[48:51], v[152:153], v[84:85], v[48:51]
	s_nop 0
	v_cndmask_b32_e32 v19, v219, v23, vcc
	v_cndmask_b32_e32 v18, v219, v22, vcc
	v_cndmask_b32_e32 v17, v219, v21, vcc
	v_cndmask_b32_e32 v16, v219, v20, vcc
	v_cmp_gt_u32_e32 vcc, s67, v198
	v_mfma_f32_16x16x32_fp8_fp8 v[52:55], v[152:153], v[92:93], v[52:55]
	s_nop 0
	v_cndmask_b32_e32 v23, v219, v27, vcc
	v_cndmask_b32_e32 v22, v219, v26, vcc
	v_cndmask_b32_e32 v21, v219, v25, vcc
	v_cndmask_b32_e32 v20, v219, v24, vcc
	v_cmp_gt_u32_e32 vcc, s67, v199
	v_mfma_f32_16x16x32_fp8_fp8 v[56:59], v[152:153], v[100:101], v[56:59]
	s_nop 0
	v_cndmask_b32_e32 v27, v219, v31, vcc
	v_cndmask_b32_e32 v26, v219, v30, vcc
	v_mfma_f32_16x16x32_fp8_fp8 v[44:47], v[154:155], v[82:83], v[44:47]
	v_cndmask_b32_e32 v25, v219, v29, vcc
	v_cndmask_b32_e32 v24, v219, v28, vcc
	v_cmp_gt_u32_e32 vcc, s67, v200
	v_mfma_f32_16x16x32_fp8_fp8 v[60:63], v[152:153], v[108:109], v[60:63]
	s_nop 0
	v_cndmask_b32_e32 v31, v219, v35, vcc
	v_cndmask_b32_e32 v30, v219, v34, vcc
	v_mfma_f32_16x16x32_fp8_fp8 v[64:67], v[150:151], v[126:127], v[64:67]
	v_cndmask_b32_e32 v29, v219, v33, vcc
	v_cndmask_b32_e32 v28, v219, v32, vcc
	v_cmp_gt_u32_e32 vcc, s67, v201
	v_mfma_f32_16x16x32_fp8_fp8 v[48:51], v[154:155], v[86:87], v[48:51]
	s_nop 0
	v_cndmask_b32_e32 v35, v219, v39, vcc
	v_cndmask_b32_e32 v34, v219, v38, vcc
	v_mfma_f32_16x16x32_fp8_fp8 v[52:55], v[154:155], v[94:95], v[52:55]
	v_cndmask_b32_e32 v33, v219, v37, vcc
	v_cndmask_b32_e32 v32, v219, v36, vcc
	v_cmp_gt_u32_e32 vcc, s67, v202
	v_mfma_f32_16x16x32_fp8_fp8 v[56:59], v[154:155], v[102:103], v[56:59]
	s_nop 0
	v_cndmask_b32_e32 v39, v219, v43, vcc
	v_cndmask_b32_e32 v38, v219, v42, vcc
	v_cndmask_b32_e32 v37, v219, v41, vcc
	v_cndmask_b32_e32 v36, v219, v40, vcc
	v_cmp_gt_u32_e32 vcc, s67, v203
	v_mfma_f32_16x16x32_fp8_fp8 v[60:63], v[154:155], v[110:111], v[60:63]
	s_nop 0
	v_cndmask_b32_e32 v43, v219, v47, vcc
	v_cndmask_b32_e32 v42, v219, v46, vcc
	v_cndmask_b32_e32 v41, v219, v45, vcc
	v_cndmask_b32_e32 v40, v219, v44, vcc
	v_cmp_gt_u32_e32 vcc, s67, v204
	s_waitcnt vmcnt(0)
	v_mfma_f32_16x16x32_fp8_fp8 v[64:67], v[152:153], v[120:121], v[64:67]
	v_cndmask_b32_e32 v47, v219, v51, vcc
	v_cndmask_b32_e32 v46, v219, v50, vcc
	v_cndmask_b32_e32 v45, v219, v49, vcc
	v_cndmask_b32_e32 v44, v219, v48, vcc
	v_cmp_gt_u32_e32 vcc, s67, v205
	s_nop 1
	v_cndmask_b32_e32 v51, v219, v55, vcc
	v_cndmask_b32_e32 v50, v219, v54, vcc
	v_cndmask_b32_e32 v49, v219, v53, vcc
	v_cndmask_b32_e32 v48, v219, v52, vcc
	v_cmp_gt_u32_e32 vcc, s67, v206
	s_nop 1
	v_cndmask_b32_e32 v55, v219, v59, vcc
	v_cndmask_b32_e32 v54, v219, v58, vcc
	v_cndmask_b32_e32 v53, v219, v57, vcc
	v_cndmask_b32_e32 v52, v219, v56, vcc
	v_cmp_gt_u32_e32 vcc, s67, v207
	s_nop 1
	v_cndmask_b32_e32 v59, v219, v63, vcc
	v_cndmask_b32_e32 v58, v219, v62, vcc
	v_cndmask_b32_e32 v57, v219, v61, vcc
	v_cndmask_b32_e32 v56, v219, v60, vcc
	v_mfma_f32_16x16x32_fp8_fp8 v[60:63], v[154:155], v[122:123], v[64:67]
	v_cmp_gt_u32_e32 vcc, s67, v208
	s_nop 6
	v_cndmask_b32_e32 v63, v219, v63, vcc
	v_cndmask_b32_e32 v62, v219, v62, vcc
	v_cndmask_b32_e32 v61, v219, v61, vcc
	v_cndmask_b32_e32 v60, v219, v60, vcc
	v_max_f32_e32 v4, v8, v8
	v_max_f32_e32 v5, v0, v0
	v_max_f32_e32 v4, v5, v4
	v_max_f32_e32 v5, v9, v9
	v_max_f32_e32 v64, v1, v1
	v_max_f32_e32 v5, v64, v5
	v_max_f32_e32 v64, v6, v6
	v_max_f32_e32 v65, v3, v3
	v_max3_f32 v4, v4, v12, v70
	v_max_f32_e32 v64, v65, v64
	v_max_f32_e32 v65, v7, v7
	v_max_f32_e32 v66, v2, v2
	v_max3_f32 v4, v4, v16, v20
	v_max_f32_e32 v65, v66, v65
	v_max3_f32 v4, v4, v24, v28
	v_and_b32_e32 v66, 64, v216
	v_max3_f32 v4, v4, v32, v36
	v_add_u32_e32 v224, 64, v66
	v_xor_b32_e32 v66, 1, v216
	v_max3_f32 v4, v4, v40, v44
	v_cmp_lt_i32_e32 vcc, v66, v224
	v_max3_f32 v4, v4, v48, v52
	v_max3_f32 v5, v5, v69, v13
	v_cndmask_b32_e32 v66, v216, v66, vcc
	v_max3_f32 v4, v4, v56, v60
	v_lshlrev_b32_e32 v66, 2, v66
	v_max3_f32 v5, v5, v17, v21
	ds_bpermute_b32 v67, v66, v4
	v_max3_f32 v5, v5, v25, v29
	v_max3_f32 v5, v5, v33, v37
	v_max3_f32 v5, v5, v41, v45
	v_max3_f32 v5, v5, v49, v53
	v_max3_f32 v64, v64, v10, v14
	v_max3_f32 v5, v5, v57, v61
	s_waitcnt lgkmcnt(0)
; __device__ __forceinline__ void dsa_attend(const h16* PROJ, const unsigned short* IDX, const int* CNT, h16* MIXA, unsigned char* shm, unsigned* bar, unsigned xcc, unsigned xrank) {
;     ...
;             f32x4 mx = sacc[0];
; #pragma unroll
;             for (int jt = 1; jt < 16; ++jt)
; #pragma unroll
;                 for (int i = 0; i < 4; ++i) mx[i] = fmaxf(mx[i], sacc[jt][i]);
; #pragma unroll
;             for (int o = 1; o < 16; o <<= 1)
; #pragma unroll
;                 for (int i = 0; i < 4; ++i) mx[i] = fmaxf(mx[i], __shfl_xor(mx[i], o));
;             f32x4 sm = (f32x4){0.f, 0.f, 0.f, 0.f};
;             const float sc = 0.08838834764831845f;
; #pragma unroll
;             for (int jt = 0; jt < 16; ++jt)
; #pragma unroll
;                 for (int i = 0; i < 4; ++i) { const float e = __expf((sacc[jt][i] - mx[i]) * sc); sacc[jt][i] = e; sm[i] += e; }
; #pragma unroll
;             for (int o = 1; o < 16; o <<= 1)
; #pragma unroll
;                 for (int i = 0; i < 4; ++i) sm[i] += __shfl_xor(sm[i], o);
	v_max_f32_e32 v67, v67, v67
	v_max3_f32 v64, v64, v18, v22
	v_max_f32_e32 v4, v4, v67
	ds_bpermute_b32 v67, v66, v5
	v_max3_f32 v64, v64, v26, v30
	v_max3_f32 v64, v64, v34, v38
	v_max3_f32 v64, v64, v42, v46
	v_max3_f32 v64, v64, v50, v54
	v_max3_f32 v65, v65, v11, v15
	v_max3_f32 v64, v64, v58, v62
	s_waitcnt lgkmcnt(0)
	v_max_f32_e32 v67, v67, v67
	v_max3_f32 v65, v65, v19, v23
	v_max_f32_e32 v5, v5, v67
	ds_bpermute_b32 v67, v66, v64
	v_max3_f32 v65, v65, v27, v31
	v_max3_f32 v65, v65, v35, v39
	v_max3_f32 v65, v65, v43, v47
	v_max3_f32 v65, v65, v51, v55
	v_max3_f32 v65, v65, v59, v63
	s_waitcnt lgkmcnt(0)
	v_max_f32_e32 v67, v67, v67
	v_max_f32_e32 v64, v64, v67
	ds_bpermute_b32 v67, v66, v65
	s_waitcnt lgkmcnt(0)
	v_max_f32_e32 v67, v67, v67
	v_max_f32_e32 v65, v65, v67
	v_xor_b32_e32 v67, 2, v216
	v_cmp_lt_i32_e32 vcc, v67, v224
	s_nop 1
	v_cndmask_b32_e32 v67, v216, v67, vcc
	v_lshlrev_b32_e32 v67, 2, v67
	ds_bpermute_b32 v68, v67, v4
	s_waitcnt lgkmcnt(0)
	v_max_f32_e32 v68, v68, v68
	v_max_f32_e32 v4, v4, v68
	ds_bpermute_b32 v68, v67, v5
	s_waitcnt lgkmcnt(0)
	v_max_f32_e32 v68, v68, v68
	v_max_f32_e32 v5, v5, v68
	ds_bpermute_b32 v68, v67, v64
	s_waitcnt lgkmcnt(0)
	v_max_f32_e32 v68, v68, v68
	v_max_f32_e32 v64, v64, v68
	ds_bpermute_b32 v68, v67, v65
	s_waitcnt lgkmcnt(0)
	v_max_f32_e32 v68, v68, v68
	v_max_f32_e32 v65, v65, v68
	v_xor_b32_e32 v68, 4, v216
	v_cmp_lt_i32_e32 vcc, v68, v224
	s_nop 1
	v_cndmask_b32_e32 v68, v216, v68, vcc
	v_lshlrev_b32_e32 v68, 2, v68
	ds_bpermute_b32 v71, v68, v4
	s_waitcnt lgkmcnt(0)
	v_max_f32_e32 v71, v71, v71
	v_max_f32_e32 v4, v4, v71
	ds_bpermute_b32 v71, v68, v5
	s_waitcnt lgkmcnt(0)
	v_max_f32_e32 v71, v71, v71
	v_max_f32_e32 v5, v5, v71
	ds_bpermute_b32 v71, v68, v64
	s_waitcnt lgkmcnt(0)
	v_max_f32_e32 v71, v71, v71
	v_max_f32_e32 v64, v64, v71
	ds_bpermute_b32 v71, v68, v65
	s_waitcnt lgkmcnt(0)
	v_max_f32_e32 v71, v71, v71
	v_max_f32_e32 v65, v65, v71
	v_xor_b32_e32 v71, 8, v216
	v_cmp_lt_i32_e32 vcc, v71, v224
	s_nop 1
	v_cndmask_b32_e32 v71, v216, v71, vcc
	v_lshlrev_b32_e32 v223, 2, v71
	ds_bpermute_b32 v71, v223, v4
	s_waitcnt lgkmcnt(0)
	v_max_f32_e32 v71, v71, v71
	v_max_f32_e32 v72, v4, v71
	ds_bpermute_b32 v4, v223, v5
	s_mov_b32 s98, 0x3e0293ee
	v_mul_f32_e32 v236, 0xbe0293ee, v72
	v_fma_f32 v0, v0, s98, v236
	v_exp_f32_e32 v0, v0
	s_waitcnt lgkmcnt(0)
	v_max_f32_e32 v4, v4, v4
	v_max_f32_e32 v73, v5, v4
	ds_bpermute_b32 v4, v223, v64
	v_mul_f32_e32 v237, 0xbe0293ee, v73
	v_fma_f32 v1, v1, s98, v237
	v_exp_f32_e32 v1, v1
	s_waitcnt lgkmcnt(0)
	v_max_f32_e32 v4, v4, v4
	v_max_f32_e32 v74, v64, v4
	ds_bpermute_b32 v4, v223, v65
	v_mul_f32_e32 v238, 0xbe0293ee, v74
	v_fma_f32 v3, v3, s98, v238
	v_fma_f32 v13, v13, s98, v237
	s_waitcnt lgkmcnt(0)
	v_max_f32_e32 v4, v4, v4
	v_max_f32_e32 v75, v65, v4
	v_mul_f32_e32 v239, 0xbe0293ee, v75
	v_fma_f32 v2, v2, s98, v239
	v_exp_f32_e32 v4, v3
	v_exp_f32_e32 v5, v2
	v_fma_f32 v2, v8, s98, v236
	v_fma_f32 v3, v9, s98, v237
	v_fma_f32 v8, v12, s98, v236
	v_fma_f32 v9, v69, s98, v237
	v_fma_f32 v12, v70, s98, v236
	v_exp_f32_e32 v2, v2
	v_exp_f32_e32 v3, v3
	v_fma_f32 v16, v16, s98, v236
	v_fma_f32 v17, v17, s98, v237
	v_exp_f32_e32 v8, v8
	v_exp_f32_e32 v9, v9
	v_fma_f32 v20, v20, s98, v236
	v_fma_f32 v21, v21, s98, v237
	v_exp_f32_e32 v12, v12
	v_exp_f32_e32 v13, v13
	v_fma_f32 v24, v24, s98, v236
	v_fma_f32 v25, v25, s98, v237
	v_exp_f32_e32 v16, v16
	v_exp_f32_e32 v17, v17
	v_fma_f32 v28, v28, s98, v236
	v_fma_f32 v29, v29, s98, v237
	v_pk_add_f32 v[64:65], v[0:1], 0 op_sel_hi:[1,0]
	v_exp_f32_e32 v20, v20
	v_exp_f32_e32 v21, v21
	v_fma_f32 v32, v32, s98, v236
	v_fma_f32 v33, v33, s98, v237
	v_pk_add_f32 v[64:65], v[2:3], v[64:65]
	v_exp_f32_e32 v24, v24
	v_exp_f32_e32 v25, v25
	v_fma_f32 v36, v36, s98, v236
	v_fma_f32 v37, v37, s98, v237
	v_pk_add_f32 v[64:65], v[8:9], v[64:65]
	v_exp_f32_e32 v28, v28
	v_exp_f32_e32 v29, v29
	v_pk_add_f32 v[64:65], v[12:13], v[64:65]
	v_fma_f32 v40, v40, s98, v236
	v_fma_f32 v41, v41, s98, v237
	v_exp_f32_e32 v32, v32
	v_exp_f32_e32 v33, v33
	v_pk_add_f32 v[64:65], v[16:17], v[64:65]
	v_fma_f32 v44, v44, s98, v236
	v_fma_f32 v45, v45, s98, v237
	v_exp_f32_e32 v36, v36
	v_exp_f32_e32 v37, v37
	v_pk_add_f32 v[64:65], v[20:21], v[64:65]
	v_fma_f32 v48, v48, s98, v236
	v_fma_f32 v49, v49, s98, v237
	v_pk_add_f32 v[64:65], v[24:25], v[64:65]
	v_exp_f32_e32 v40, v40
	v_exp_f32_e32 v41, v41
	v_fma_f32 v52, v52, s98, v236
	v_fma_f32 v53, v53, s98, v237
	v_pk_add_f32 v[64:65], v[28:29], v[64:65]
	v_exp_f32_e32 v44, v44
	v_exp_f32_e32 v45, v45
	v_fma_f32 v56, v56, s98, v236
	v_fma_f32 v57, v57, s98, v237
	v_pk_add_f32 v[64:65], v[32:33], v[64:65]
	v_exp_f32_e32 v48, v48
	v_exp_f32_e32 v49, v49
	v_fma_f32 v60, v60, s98, v236
	v_fma_f32 v61, v61, s98, v237
	v_pk_add_f32 v[64:65], v[36:37], v[64:65]
	v_exp_f32_e32 v52, v52
	v_exp_f32_e32 v53, v53
	v_exp_f32_e32 v56, v56
	v_exp_f32_e32 v57, v57
	v_pk_add_f32 v[64:65], v[40:41], v[64:65]
	v_fma_f32 v6, v6, s98, v238
	v_fma_f32 v7, v7, s98, v239
	v_exp_f32_e32 v60, v60
	v_exp_f32_e32 v61, v61
	v_pk_add_f32 v[64:65], v[44:45], v[64:65]
	v_fma_f32 v10, v10, s98, v238
	v_fma_f32 v11, v11, s98, v239
	v_pk_add_f32 v[64:65], v[48:49], v[64:65]
	v_fma_f32 v14, v14, s98, v238
	v_fma_f32 v15, v15, s98, v239
	v_pk_add_f32 v[64:65], v[52:53], v[64:65]
	v_exp_f32_e32 v6, v6
	v_exp_f32_e32 v7, v7
	v_fma_f32 v18, v18, s98, v238
	v_fma_f32 v19, v19, s98, v239
	v_pk_add_f32 v[64:65], v[56:57], v[64:65]
	v_exp_f32_e32 v10, v10
	v_exp_f32_e32 v11, v11
	v_fma_f32 v22, v22, s98, v238
	v_fma_f32 v23, v23, s98, v239
	v_pk_add_f32 v[64:65], v[60:61], v[64:65]
	v_exp_f32_e32 v14, v14
	v_exp_f32_e32 v15, v15
	v_fma_f32 v26, v26, s98, v238
	v_fma_f32 v27, v27, s98, v239
	ds_bpermute_b32 v72, v66, v64
	ds_bpermute_b32 v73, v66, v65
	v_exp_f32_e32 v18, v18
	v_exp_f32_e32 v19, v19
	v_fma_f32 v30, v30, s98, v238
	v_fma_f32 v31, v31, s98, v239
	v_pk_add_f32 v[70:71], v[4:5], 0 op_sel_hi:[1,0]
	v_exp_f32_e32 v22, v22
	v_exp_f32_e32 v23, v23
	v_fma_f32 v34, v34, s98, v238
	v_fma_f32 v35, v35, s98, v239
	v_pk_add_f32 v[70:71], v[6:7], v[70:71]
	v_exp_f32_e32 v26, v26
	v_exp_f32_e32 v27, v27
	v_fma_f32 v38, v38, s98, v238
	v_fma_f32 v39, v39, s98, v239
	v_pk_add_f32 v[70:71], v[10:11], v[70:71]
	v_exp_f32_e32 v30, v30
	v_exp_f32_e32 v31, v31
	v_pk_add_f32 v[70:71], v[14:15], v[70:71]
	v_fma_f32 v42, v42, s98, v238
	v_fma_f32 v43, v43, s98, v239
	v_exp_f32_e32 v34, v34
	v_exp_f32_e32 v35, v35
	v_pk_add_f32 v[70:71], v[18:19], v[70:71]
	v_fma_f32 v46, v46, s98, v238
	v_fma_f32 v47, v47, s98, v239
	s_waitcnt lgkmcnt(0)
; __device__ __forceinline__ void dsa_attend(const h16* PROJ, const unsigned short* IDX, const int* CNT, h16* MIXA, unsigned char* shm, unsigned* bar, unsigned xcc, unsigned xrank) {
;     ...
;             f32x4 sm = (f32x4){0.f, 0.f, 0.f, 0.f};
;             const float sc = 0.08838834764831845f;
; #pragma unroll
;             for (int jt = 0; jt < 16; ++jt)
; #pragma unroll
;                 for (int i = 0; i < 4; ++i) { const float e = __expf((sacc[jt][i] - mx[i]) * sc); sacc[jt][i] = e; sm[i] += e; }
; #pragma unroll
;             for (int o = 1; o < 16; o <<= 1)
; #pragma unroll
;                 for (int i = 0; i < 4; ++i) sm[i] += __shfl_xor(sm[i], o);
;             f32x4 inv;
; #pragma unroll
;             for (int i = 0; i < 4; ++i) inv[i] = 1.f / sm[i];
;             if (fq == 0) {
; #pragma unroll
;                 for (int jt = 0; jt < 16; ++jt) *(f32x4*)(Pl + ((size_t)wid * 256 + 16 * jt + fr) * 4) = sacc[jt] * inv;
;             }
;             asm volatile("s_waitcnt lgkmcnt(0)" ::: "memory");
	v_pk_add_f32 v[64:65], v[64:65], v[72:73]
	v_exp_f32_e32 v38, v38
	v_exp_f32_e32 v39, v39
	v_pk_add_f32 v[70:71], v[22:23], v[70:71]
	v_fma_f32 v50, v50, s98, v238
	v_fma_f32 v51, v51, s98, v239
	ds_bpermute_b32 v72, v67, v64
	ds_bpermute_b32 v73, v67, v65
	v_pk_add_f32 v[70:71], v[26:27], v[70:71]
	v_exp_f32_e32 v42, v42
	v_exp_f32_e32 v43, v43
	v_fma_f32 v54, v54, s98, v238
	v_fma_f32 v55, v55, s98, v239
	v_pk_add_f32 v[70:71], v[30:31], v[70:71]
	v_exp_f32_e32 v46, v46
	v_exp_f32_e32 v47, v47
	v_fma_f32 v58, v58, s98, v238
	v_fma_f32 v59, v59, s98, v239
	v_pk_add_f32 v[70:71], v[34:35], v[70:71]
	v_exp_f32_e32 v50, v50
	v_exp_f32_e32 v51, v51
	v_fma_f32 v62, v62, s98, v238
	v_fma_f32 v63, v63, s98, v239
	v_pk_add_f32 v[70:71], v[38:39], v[70:71]
	v_exp_f32_e32 v54, v54
	v_exp_f32_e32 v55, v55
	v_exp_f32_e32 v58, v58
	v_exp_f32_e32 v59, v59
	s_waitcnt lgkmcnt(0)
	v_pk_add_f32 v[64:65], v[64:65], v[72:73]
	v_pk_add_f32 v[70:71], v[42:43], v[70:71]
	v_exp_f32_e32 v62, v62
	v_exp_f32_e32 v63, v63
	ds_bpermute_b32 v72, v68, v64
	ds_bpermute_b32 v73, v68, v65
	v_pk_add_f32 v[70:71], v[46:47], v[70:71]
	s_waitcnt lgkmcnt(0)
	v_pk_add_f32 v[64:65], v[64:65], v[72:73]
	v_pk_add_f32 v[70:71], v[50:51], v[70:71]
	s_nop 0
	v_pk_add_f32 v[70:71], v[54:55], v[70:71]
	s_nop 0
	v_pk_add_f32 v[70:71], v[58:59], v[70:71]
	s_nop 0
	v_pk_add_f32 v[70:71], v[62:63], v[70:71]
	ds_bpermute_b32 v72, v66, v70
	ds_bpermute_b32 v73, v66, v71
	s_waitcnt lgkmcnt(0)
	v_pk_add_f32 v[70:71], v[70:71], v[72:73]
	ds_bpermute_b32 v66, v67, v70
	ds_bpermute_b32 v67, v67, v71
	s_waitcnt lgkmcnt(0)
	v_pk_add_f32 v[66:67], v[70:71], v[66:67]
	ds_bpermute_b32 v70, v68, v66
	ds_bpermute_b32 v71, v68, v67
	s_waitcnt lgkmcnt(0)
	v_pk_add_f32 v[68:69], v[66:67], v[70:71]
	ds_bpermute_b32 v66, v223, v64
	ds_bpermute_b32 v67, v223, v65
	ds_bpermute_b32 v70, v223, v68
	ds_bpermute_b32 v71, v223, v69
	s_and_saveexec_b64 s[50:51], s[46:47]
	s_cbranch_execz .LBB0_848
	s_waitcnt lgkmcnt(2)
	v_pk_add_f32 v[64:65], v[64:65], v[66:67]
	s_waitcnt lgkmcnt(0)
	v_pk_add_f32 v[68:69], v[68:69], v[70:71]
	v_div_scale_f32 v66, s[60:61], v65, v65, 1.0
	v_rcp_f32_e32 v67, v66
	s_nop 0
	v_fma_f32 v70, -v66, v67, 1.0
	v_fmac_f32_e32 v67, v70, v67
	v_div_scale_f32 v70, vcc, 1.0, v65, 1.0
	v_mul_f32_e32 v71, v70, v67
	v_fma_f32 v72, -v66, v71, v70
	v_fmac_f32_e32 v71, v72, v67
	v_fma_f32 v66, -v66, v71, v70
	v_div_fmas_f32 v66, v66, v67, v71
	v_div_fixup_f32 v71, v66, v65, 1.0
	v_div_scale_f32 v65, s[60:61], v64, v64, 1.0
	v_rcp_f32_e32 v66, v65
	s_nop 0
	v_fma_f32 v67, -v65, v66, 1.0
	v_fmac_f32_e32 v66, v67, v66
	v_div_scale_f32 v67, vcc, 1.0, v64, 1.0
	v_mul_f32_e32 v70, v67, v66
	v_fma_f32 v72, -v65, v70, v67
	v_fmac_f32_e32 v70, v72, v66
	v_fma_f32 v65, -v65, v70, v67
	v_div_fmas_f32 v65, v65, v66, v70
	v_div_fixup_f32 v70, v65, v64, 1.0
	v_div_scale_f32 v64, s[60:61], v69, v69, 1.0
	v_rcp_f32_e32 v65, v64
	v_pk_mul_f32 v[2:3], v[2:3], v[70:71]
	v_fma_f32 v66, -v64, v65, 1.0
	v_fmac_f32_e32 v65, v66, v65
	v_div_scale_f32 v66, vcc, 1.0, v69, 1.0
	v_mul_f32_e32 v67, v66, v65
	v_fma_f32 v72, -v64, v67, v66
	v_fmac_f32_e32 v67, v72, v65
	v_fma_f32 v64, -v64, v67, v66
	v_div_fmas_f32 v64, v64, v65, v67
	v_div_fixup_f32 v69, v64, v69, 1.0
	v_div_scale_f32 v64, s[60:61], v68, v68, 1.0
	v_rcp_f32_e32 v65, v64
	s_nop 0
	v_fma_f32 v66, -v64, v65, 1.0
	v_fmac_f32_e32 v65, v66, v65
	v_div_scale_f32 v66, vcc, 1.0, v68, 1.0
	v_mul_f32_e32 v67, v66, v65
	v_fma_f32 v72, -v64, v67, v66
	v_fmac_f32_e32 v67, v72, v65
	v_fma_f32 v64, -v64, v67, v66
	v_div_fmas_f32 v64, v64, v65, v67
	v_div_fixup_f32 v68, v64, v68, 1.0
	v_pk_mul_f32 v[66:67], v[4:5], v[68:69]
	v_pk_mul_f32 v[4:5], v[6:7], v[68:69]
	v_pk_mul_f32 v[64:65], v[0:1], v[70:71]
	ds_write_b128 v210, v[2:5] offset:256
	v_pk_mul_f32 v[2:3], v[10:11], v[68:69]
	v_pk_mul_f32 v[0:1], v[8:9], v[70:71]
	ds_write_b128 v210, v[0:3] offset:512
	v_pk_mul_f32 v[2:3], v[14:15], v[68:69]
	v_pk_mul_f32 v[0:1], v[12:13], v[70:71]
	ds_write_b128 v210, v[0:3] offset:768
	v_pk_mul_f32 v[2:3], v[18:19], v[68:69]
	v_pk_mul_f32 v[0:1], v[16:17], v[70:71]
	ds_write_b128 v210, v[0:3] offset:1024
	v_pk_mul_f32 v[2:3], v[22:23], v[68:69]
	v_pk_mul_f32 v[0:1], v[20:21], v[70:71]
	ds_write_b128 v210, v[0:3] offset:1280
	v_pk_mul_f32 v[2:3], v[26:27], v[68:69]
	v_pk_mul_f32 v[0:1], v[24:25], v[70:71]
	ds_write_b128 v210, v[0:3] offset:1536
	v_pk_mul_f32 v[2:3], v[30:31], v[68:69]
	v_pk_mul_f32 v[0:1], v[28:29], v[70:71]
	ds_write_b128 v210, v[0:3] offset:1792
	v_pk_mul_f32 v[2:3], v[34:35], v[68:69]
	v_pk_mul_f32 v[0:1], v[32:33], v[70:71]
	ds_write_b128 v210, v[0:3] offset:2048
	v_pk_mul_f32 v[2:3], v[38:39], v[68:69]
	v_pk_mul_f32 v[0:1], v[36:37], v[70:71]
	ds_write_b128 v210, v[0:3] offset:2304
	v_pk_mul_f32 v[2:3], v[42:43], v[68:69]
	v_pk_mul_f32 v[0:1], v[40:41], v[70:71]
	ds_write_b128 v210, v[0:3] offset:2560
	v_pk_mul_f32 v[2:3], v[46:47], v[68:69]
	v_pk_mul_f32 v[0:1], v[44:45], v[70:71]
	ds_write_b128 v210, v[0:3] offset:2816
	v_pk_mul_f32 v[2:3], v[50:51], v[68:69]
	v_pk_mul_f32 v[0:1], v[48:49], v[70:71]
	ds_write_b128 v210, v[0:3] offset:3072
	v_pk_mul_f32 v[2:3], v[54:55], v[68:69]
	v_pk_mul_f32 v[0:1], v[52:53], v[70:71]
	ds_write_b128 v210, v[0:3] offset:3328
	v_pk_mul_f32 v[2:3], v[58:59], v[68:69]
	v_pk_mul_f32 v[0:1], v[56:57], v[70:71]
	ds_write_b128 v210, v[0:3] offset:3584
	v_pk_mul_f32 v[2:3], v[62:63], v[68:69]
	v_pk_mul_f32 v[0:1], v[60:61], v[70:71]
	ds_write_b128 v210, v[64:67]
	ds_write_b128 v210, v[0:3] offset:3840
